# GEMM mainloop: LDS staging writes moved to MFMA groups 11-14 (2 per group) with the global-load block right after and two MFMA groups behind it
# speedup vs baseline: 1.0170x; 1.0150x over previous
; #define MFMA16(a, b, c) __builtin_amdgcn_mfma_f32_16x16x32_bf16((a), (b), (c), 0, 0, 0)
;     ...
;     bf16_t* sA = sm + (q & 1) * STG; bf16_t* sB = sA + BM * LDSS;
;     constexpr int FA = MI < 4 ? MI : 4, HG = MI / FA, NG = 2 * HG;
;     bf16x8 fb[2][4], fa[2][FA];
;     const bf16_t* pA = sA + (wm * MI * 16) * LDSS + fro; const bf16_t* pB = sB + (wn * 64) * LDSS + fro;
; #pragma unroll
;     for (int j = 0; j < 4; ++j) fb[0][j] = *(const bf16x8*)(pB + (j * 16) * LDSS);
; #pragma unroll
;     for (int i = 0; i < FA; ++i) fa[0][i] = *(const bf16x8*)(pA + (i * 16) * LDSS);
;     __builtin_amdgcn_sched_barrier(0);
;     if (q + 1 < Q) {
;       bf16_t* nA = sm + ((q + 1) & 1) * STG; bf16_t* nB = nA + BM * LDSS;
; #pragma unroll
;       for (int i = 0; i < AR; ++i) *(u32x4*)(nA + (lr + 64 * i) * LDSS + lc) = ra[i];
; #pragma unroll
;       for (int i = 0; i < BR; ++i) *(u32x4*)(nB + (lr + 64 * i) * LDSS + lc) = rb[i];
;     }
;     if (q + 2 < Q) {
;       int kt2 = kt + 2;
;       if (kt2 >= nk) { kt2 -= nk; if (kt2 == 0) set_offs(jt + 1); }
;       const char* gk = gb + kt2 * 128;
; #pragma unroll
;       for (int i = 0; i < AR; ++i) ra[i] = *(const u32x4*)(gk + ap[i]);
; #pragma unroll
;       for (int i = 0; i < BR; ++i) rb[i] = *(const u32x4*)(gk + bp[i]);
;     }
;     __builtin_amdgcn_sched_barrier(0);
;     {
; #pragma unroll
;       for (int gi = 0; gi < NG; ++gi) {
;         const int ks = gi / HG;
;         if (gi + 1 < NG) {
;           const int ks1 = (gi + 1) / HG, h1 = (gi + 1) % HG;
;           if (ks1 != ks) {
; #pragma unroll
;             for (int j = 0; j < 4; ++j) fb[ks1 & 1][j] = *(const bf16x8*)(pB + (j * 16) * LDSS + ks1 * 32);
;           }
; #pragma unroll
;           for (int i = 0; i < FA; ++i) fa[(gi + 1) & 1][i] = *(const bf16x8*)(pA + ((h1 * FA + i) * 16) * LDSS + ks1 * 32);
;         }
;         const int h = gi % HG;
; #pragma unroll
;         for (int i = 0; i < FA; ++i)
; #pragma unroll
;           for (int j = 0; j < 4; ++j)
;             acc[h * FA + i][j] = NAT ? MFMA16(fa[gi & 1][i], fb[ks & 1][j], acc[h * FA + i][j]) : MFMA16(fb[ks & 1][j], fa[gi & 1][i], acc[h * FA + i][j]);
;         __builtin_amdgcn_sched_barrier(0);
.LBB0_463:
	s_bitcmp1_b32 s0, 0
	s_cselect_b32 s1, 0x12000, 0
	v_add3_u32 v243, s1, v237, v242
	v_add3_u32 v192, s1, v236, v242
	ds_read_b128 v[168:171], v243 offset:36864
	ds_read_b128 v[188:191], v192
	ds_read_b128 v[172:175], v243 offset:39168
	ds_read_b128 v[164:167], v243 offset:41472
	ds_read_b128 v[160:163], v243 offset:43776
	ds_read_b128 v[184:187], v192 offset:2304
	ds_read_b128 v[180:183], v192 offset:4608
	ds_read_b128 v[176:179], v192 offset:6912
	s_add_i32 s24, s0, 1
	s_waitcnt lgkmcnt(6)
	v_mfma_f32_16x16x32_bf16 v[156:159], v[168:171], v[188:191], v[156:159]
	s_waitcnt lgkmcnt(5)
	v_mfma_f32_16x16x32_bf16 v[152:155], v[172:175], v[188:191], v[152:155]
	s_waitcnt lgkmcnt(4)
	v_mfma_f32_16x16x32_bf16 v[148:151], v[164:167], v[188:191], v[148:151]
	s_waitcnt lgkmcnt(3)
	v_mfma_f32_16x16x32_bf16 v[144:147], v[160:163], v[188:191], v[144:147]
	ds_read_b128 v[216:219], v192 offset:9216
	ds_read_b128 v[188:191], v192 offset:11520
	s_waitcnt lgkmcnt(4)
	v_mfma_f32_16x16x32_bf16 v[140:143], v[168:171], v[184:187], v[140:143]
	v_mfma_f32_16x16x32_bf16 v[136:139], v[172:175], v[184:187], v[136:139]
	v_mfma_f32_16x16x32_bf16 v[132:135], v[164:167], v[184:187], v[132:135]
	v_mfma_f32_16x16x32_bf16 v[128:131], v[160:163], v[184:187], v[128:131]
	ds_read_b128 v[184:187], v192 offset:13824
	s_waitcnt lgkmcnt(4)
	v_mfma_f32_16x16x32_bf16 v[124:127], v[168:171], v[180:183], v[124:127]
	v_mfma_f32_16x16x32_bf16 v[120:123], v[172:175], v[180:183], v[120:123]
	v_mfma_f32_16x16x32_bf16 v[116:119], v[164:167], v[180:183], v[116:119]
	v_mfma_f32_16x16x32_bf16 v[112:115], v[160:163], v[180:183], v[112:115]
	ds_read_b128 v[180:183], v192 offset:16128
	s_waitcnt lgkmcnt(4)
	v_mfma_f32_16x16x32_bf16 v[108:111], v[168:171], v[176:179], v[108:111]
	v_mfma_f32_16x16x32_bf16 v[104:107], v[172:175], v[176:179], v[104:107]
	v_mfma_f32_16x16x32_bf16 v[100:103], v[164:167], v[176:179], v[100:103]
	v_mfma_f32_16x16x32_bf16 v[96:99], v[160:163], v[176:179], v[96:99]
	ds_read_b128 v[176:179], v243 offset:36928
	s_waitcnt lgkmcnt(4)
	v_mfma_f32_16x16x32_bf16 v[92:95], v[168:171], v[216:219], v[92:95]
	v_mfma_f32_16x16x32_bf16 v[88:91], v[172:175], v[216:219], v[88:91]
	v_mfma_f32_16x16x32_bf16 v[84:87], v[164:167], v[216:219], v[84:87]
	v_mfma_f32_16x16x32_bf16 v[80:83], v[160:163], v[216:219], v[80:83]
	ds_read_b128 v[216:219], v243 offset:39232
	s_waitcnt lgkmcnt(4)
	v_mfma_f32_16x16x32_bf16 v[76:79], v[168:171], v[188:191], v[76:79]
	v_mfma_f32_16x16x32_bf16 v[72:75], v[172:175], v[188:191], v[72:75]
	v_mfma_f32_16x16x32_bf16 v[68:71], v[164:167], v[188:191], v[68:71]
	v_mfma_f32_16x16x32_bf16 v[64:67], v[160:163], v[188:191], v[64:67]
	ds_read_b128 v[188:191], v243 offset:41536
	s_waitcnt lgkmcnt(4)
	v_mfma_f32_16x16x32_bf16 v[60:63], v[168:171], v[184:187], v[60:63]
	v_mfma_f32_16x16x32_bf16 v[56:59], v[172:175], v[184:187], v[56:59]
	v_mfma_f32_16x16x32_bf16 v[52:55], v[164:167], v[184:187], v[52:55]
	v_mfma_f32_16x16x32_bf16 v[48:51], v[160:163], v[184:187], v[48:51]
	ds_read_b128 v[184:187], v243 offset:43840
	ds_read_b128 v[244:247], v192 offset:64
	s_waitcnt lgkmcnt(5)
	v_mfma_f32_16x16x32_bf16 v[44:47], v[168:171], v[180:183], v[44:47]
	ds_read_b128 v[168:171], v192 offset:2368
	v_mfma_f32_16x16x32_bf16 v[40:43], v[172:175], v[180:183], v[40:43]
	ds_read_b128 v[172:175], v192 offset:4672
	v_mfma_f32_16x16x32_bf16 v[36:39], v[164:167], v[180:183], v[36:39]
	ds_read_b128 v[164:167], v192 offset:6976
	v_mfma_f32_16x16x32_bf16 v[8:11], v[160:163], v[180:183], v[8:11]
	ds_read_b128 v[160:163], v192 offset:9280
	ds_read_b128 v[180:183], v192 offset:11584
	s_waitcnt lgkmcnt(5)
	v_mfma_f32_16x16x32_bf16 v[156:159], v[176:179], v[244:247], v[156:159]
	v_mfma_f32_16x16x32_bf16 v[152:155], v[216:219], v[244:247], v[152:155]
	v_mfma_f32_16x16x32_bf16 v[148:151], v[188:191], v[244:247], v[148:151]
	v_mfma_f32_16x16x32_bf16 v[144:147], v[184:187], v[244:247], v[144:147]
	ds_read_b128 v[244:247], v192 offset:13888
	s_waitcnt lgkmcnt(5)
	v_mfma_f32_16x16x32_bf16 v[140:143], v[176:179], v[168:171], v[140:143]
	v_mfma_f32_16x16x32_bf16 v[136:139], v[216:219], v[168:171], v[136:139]
	v_mfma_f32_16x16x32_bf16 v[132:135], v[188:191], v[168:171], v[132:135]
	v_mfma_f32_16x16x32_bf16 v[128:131], v[184:187], v[168:171], v[128:131]
	ds_read_b128 v[168:171], v192 offset:16192
	s_waitcnt lgkmcnt(5)
	v_mfma_f32_16x16x32_bf16 v[124:127], v[176:179], v[172:175], v[124:127]
	v_mfma_f32_16x16x32_bf16 v[120:123], v[216:219], v[172:175], v[120:123]
	v_mfma_f32_16x16x32_bf16 v[116:119], v[188:191], v[172:175], v[116:119]
	v_mfma_f32_16x16x32_bf16 v[112:115], v[184:187], v[172:175], v[112:115]
	s_bitcmp1_b32 s24, 0
	s_cselect_b32 s1, 0x12000, 0
	v_or_b32_e32 v172, s1, v195
	v_add_u32_e32 v172, v172, v199
	s_waitcnt vmcnt(7)
	ds_write_b128 v172, v[0:3]
	s_waitcnt vmcnt(6)
	ds_write_b128 v172, v[4:7] offset:9216
	s_waitcnt lgkmcnt(6)
	v_mfma_f32_16x16x32_bf16 v[108:111], v[176:179], v[164:167], v[108:111]
	v_mfma_f32_16x16x32_bf16 v[104:107], v[216:219], v[164:167], v[104:107]
	v_mfma_f32_16x16x32_bf16 v[100:103], v[188:191], v[164:167], v[100:103]
	v_mfma_f32_16x16x32_bf16 v[96:99], v[184:187], v[164:167], v[96:99]
	s_waitcnt vmcnt(5)
	ds_write_b128 v172, v[12:15] offset:18432
	s_waitcnt vmcnt(4)
	ds_write_b128 v172, v[16:19] offset:27648
	s_waitcnt lgkmcnt(7)
	v_mfma_f32_16x16x32_bf16 v[92:95], v[176:179], v[160:163], v[92:95]
	v_mfma_f32_16x16x32_bf16 v[88:91], v[216:219], v[160:163], v[88:91]
	v_mfma_f32_16x16x32_bf16 v[84:87], v[188:191], v[160:163], v[84:87]
	v_mfma_f32_16x16x32_bf16 v[80:83], v[184:187], v[160:163], v[80:83]
	s_waitcnt vmcnt(3)
	ds_write_b128 v172, v[20:23] offset:36864
	s_waitcnt vmcnt(2)
	ds_write_b128 v172, v[24:27] offset:46080
	s_waitcnt lgkmcnt(8)
	v_mfma_f32_16x16x32_bf16 v[76:79], v[176:179], v[180:183], v[76:79]
	v_mfma_f32_16x16x32_bf16 v[72:75], v[216:219], v[180:183], v[72:75]
	v_mfma_f32_16x16x32_bf16 v[68:71], v[188:191], v[180:183], v[68:71]
	v_mfma_f32_16x16x32_bf16 v[64:67], v[184:187], v[180:183], v[64:67]
	s_waitcnt vmcnt(1)
	ds_write_b128 v172, v[28:31] offset:55296
	s_waitcnt vmcnt(0)
	ds_write_b128 v172, v[32:35] offset:64512

; #define MFMA16(a, b, c) __builtin_amdgcn_mfma_f32_16x16x32_bf16((a), (b), (c), 0, 0, 0)
;     ...
;       for (int gi = 0; gi < NG; ++gi) {
;         const int ks = gi / HG;
;         if (gi + 1 < NG) {
;           const int ks1 = (gi + 1) / HG, h1 = (gi + 1) % HG;
;           if (ks1 != ks) {
; #pragma unroll
;             for (int j = 0; j < 4; ++j) fb[ks1 & 1][j] = *(const bf16x8*)(pB + (j * 16) * LDSS + ks1 * 32);
;           }
; #pragma unroll
;           for (int i = 0; i < FA; ++i) fa[(gi + 1) & 1][i] = *(const bf16x8*)(pA + ((h1 * FA + i) * 16) * LDSS + ks1 * 32);
;         }
;         const int h = gi % HG;
; #pragma unroll
;         for (int i = 0; i < FA; ++i)
; #pragma unroll
;           for (int j = 0; j < 4; ++j)
;             acc[h * FA + i][j] = NAT ? MFMA16(fa[gi & 1][i], fb[ks & 1][j], acc[h * FA + i][j]) : MFMA16(fb[ks & 1][j], fa[gi & 1][i], acc[h * FA + i][j]);
;         __builtin_amdgcn_sched_barrier(0);
;       }
;     }
;     if (kt == nk - 1) {
.LBB0_475:
	s_waitcnt lgkmcnt(9)
	v_mfma_f32_16x16x32_bf16 v[60:63], v[176:179], v[244:247], v[60:63]
	v_mfma_f32_16x16x32_bf16 v[56:59], v[216:219], v[244:247], v[56:59]
	v_mfma_f32_16x16x32_bf16 v[52:55], v[188:191], v[244:247], v[52:55]
	v_mfma_f32_16x16x32_bf16 v[48:51], v[184:187], v[244:247], v[48:51]
	s_waitcnt lgkmcnt(8)
	v_mfma_f32_16x16x32_bf16 v[44:47], v[176:179], v[168:171], v[44:47]
	v_mfma_f32_16x16x32_bf16 v[40:43], v[216:219], v[168:171], v[40:43]
	v_mfma_f32_16x16x32_bf16 v[36:39], v[188:191], v[168:171], v[36:39]
	v_mfma_f32_16x16x32_bf16 v[8:11], v[184:187], v[168:171], v[8:11]
	s_waitcnt lgkmcnt(0)
	s_cmp_lg_u32 s25, 15
	s_mov_b64 s[0:1], -1
	s_cbranch_scc0 .LBB0_477
	s_add_i32 s25, s25, 1
	s_mov_b64 s[0:1], 0

; #define MFMA16(a, b, c) __builtin_amdgcn_mfma_f32_16x16x32_bf16((a), (b), (c), 0, 0, 0)
;     ...
;     bf16_t* sA = sm + (q & 1) * STG; bf16_t* sB = sA + BM * LDSS;
;     constexpr int FA = MI < 4 ? MI : 4, HG = MI / FA, NG = 2 * HG;
;     bf16x8 fb[2][4], fa[2][FA];
;     const bf16_t* pA = sA + (wm * MI * 16) * LDSS + fro; const bf16_t* pB = sB + (wn * 64) * LDSS + fro;
; #pragma unroll
;     for (int j = 0; j < 4; ++j) fb[0][j] = *(const bf16x8*)(pB + (j * 16) * LDSS);
; #pragma unroll
;     for (int i = 0; i < FA; ++i) fa[0][i] = *(const bf16x8*)(pA + (i * 16) * LDSS);
;     __builtin_amdgcn_sched_barrier(0);
;     if (q + 1 < Q) {
;       bf16_t* nA = sm + ((q + 1) & 1) * STG; bf16_t* nB = nA + BM * LDSS;
; #pragma unroll
;       for (int i = 0; i < AR; ++i) *(u32x4*)(nA + (lr + 64 * i) * LDSS + lc) = ra[i];
; #pragma unroll
;       for (int i = 0; i < BR; ++i) *(u32x4*)(nB + (lr + 64 * i) * LDSS + lc) = rb[i];
;     }
;     if (q + 2 < Q) {
;       int kt2 = kt + 2;
;       if (kt2 >= nk) { kt2 -= nk; if (kt2 == 0) set_offs(jt + 1); }
;       const char* gk = gb + kt2 * 128;
; #pragma unroll
;       for (int i = 0; i < AR; ++i) ra[i] = *(const u32x4*)(gk + ap[i]);
; #pragma unroll
;       for (int i = 0; i < BR; ++i) rb[i] = *(const u32x4*)(gk + bp[i]);
;     }
;     __builtin_amdgcn_sched_barrier(0);
;     {
; #pragma unroll
;       for (int gi = 0; gi < NG; ++gi) {
;         const int ks = gi / HG;
;         if (gi + 1 < NG) {
;           const int ks1 = (gi + 1) / HG, h1 = (gi + 1) % HG;
;           if (ks1 != ks) {
; #pragma unroll
;             for (int j = 0; j < 4; ++j) fb[ks1 & 1][j] = *(const bf16x8*)(pB + (j * 16) * LDSS + ks1 * 32);
;           }
; #pragma unroll
;           for (int i = 0; i < FA; ++i) fa[(gi + 1) & 1][i] = *(const bf16x8*)(pA + ((h1 * FA + i) * 16) * LDSS + ks1 * 32);
;         }
;         const int h = gi % HG;
; #pragma unroll
;         for (int i = 0; i < FA; ++i)
; #pragma unroll
;           for (int j = 0; j < 4; ++j)
;             acc[h * FA + i][j] = NAT ? MFMA16(fa[gi & 1][i], fb[ks & 1][j], acc[h * FA + i][j]) : MFMA16(fb[ks & 1][j], fa[gi & 1][i], acc[h * FA + i][j]);
;         __builtin_amdgcn_sched_barrier(0);
.LBB0_524:
	s_bitcmp1_b32 s0, 0
	s_cselect_b32 s1, 0x12000, 0
	v_add3_u32 v248, s1, v242, v247
	v_add3_u32 v192, s1, v241, v247
	ds_read_b128 v[168:171], v248 offset:36864
	ds_read_b128 v[188:191], v192
	ds_read_b128 v[172:175], v248 offset:39168
	ds_read_b128 v[164:167], v248 offset:41472
	ds_read_b128 v[160:163], v248 offset:43776
	ds_read_b128 v[184:187], v192 offset:2304
	ds_read_b128 v[180:183], v192 offset:4608
	ds_read_b128 v[176:179], v192 offset:6912
	s_add_i32 s25, s0, 1
	s_waitcnt lgkmcnt(6)
	v_mfma_f32_16x16x32_bf16 v[156:159], v[168:171], v[188:191], v[156:159]
	s_waitcnt lgkmcnt(5)
	v_mfma_f32_16x16x32_bf16 v[152:155], v[172:175], v[188:191], v[152:155]
	s_waitcnt lgkmcnt(4)
	v_mfma_f32_16x16x32_bf16 v[148:151], v[164:167], v[188:191], v[148:151]
	s_waitcnt lgkmcnt(3)
	v_mfma_f32_16x16x32_bf16 v[144:147], v[160:163], v[188:191], v[144:147]
	ds_read_b128 v[216:219], v192 offset:9216
	ds_read_b128 v[188:191], v192 offset:11520
	s_waitcnt lgkmcnt(4)
	v_mfma_f32_16x16x32_bf16 v[140:143], v[168:171], v[184:187], v[140:143]
	v_mfma_f32_16x16x32_bf16 v[136:139], v[172:175], v[184:187], v[136:139]
	v_mfma_f32_16x16x32_bf16 v[132:135], v[164:167], v[184:187], v[132:135]
	v_mfma_f32_16x16x32_bf16 v[128:131], v[160:163], v[184:187], v[128:131]
	ds_read_b128 v[184:187], v192 offset:13824
	s_waitcnt lgkmcnt(4)
	v_mfma_f32_16x16x32_bf16 v[124:127], v[168:171], v[180:183], v[124:127]
	v_mfma_f32_16x16x32_bf16 v[120:123], v[172:175], v[180:183], v[120:123]
	v_mfma_f32_16x16x32_bf16 v[116:119], v[164:167], v[180:183], v[116:119]
	v_mfma_f32_16x16x32_bf16 v[112:115], v[160:163], v[180:183], v[112:115]
	ds_read_b128 v[180:183], v192 offset:16128
	s_waitcnt lgkmcnt(4)
	v_mfma_f32_16x16x32_bf16 v[108:111], v[168:171], v[176:179], v[108:111]
	v_mfma_f32_16x16x32_bf16 v[104:107], v[172:175], v[176:179], v[104:107]
	v_mfma_f32_16x16x32_bf16 v[100:103], v[164:167], v[176:179], v[100:103]
	v_mfma_f32_16x16x32_bf16 v[96:99], v[160:163], v[176:179], v[96:99]
	ds_read_b128 v[176:179], v248 offset:36928
	s_waitcnt lgkmcnt(4)
	v_mfma_f32_16x16x32_bf16 v[92:95], v[168:171], v[216:219], v[92:95]
	v_mfma_f32_16x16x32_bf16 v[88:91], v[172:175], v[216:219], v[88:91]
	v_mfma_f32_16x16x32_bf16 v[84:87], v[164:167], v[216:219], v[84:87]
	v_mfma_f32_16x16x32_bf16 v[80:83], v[160:163], v[216:219], v[80:83]
	ds_read_b128 v[216:219], v248 offset:39232
	s_waitcnt lgkmcnt(4)
	v_mfma_f32_16x16x32_bf16 v[76:79], v[168:171], v[188:191], v[76:79]
	v_mfma_f32_16x16x32_bf16 v[72:75], v[172:175], v[188:191], v[72:75]
	v_mfma_f32_16x16x32_bf16 v[68:71], v[164:167], v[188:191], v[68:71]
	v_mfma_f32_16x16x32_bf16 v[64:67], v[160:163], v[188:191], v[64:67]
	ds_read_b128 v[188:191], v248 offset:41536
	s_waitcnt lgkmcnt(4)
	v_mfma_f32_16x16x32_bf16 v[60:63], v[168:171], v[184:187], v[60:63]
	v_mfma_f32_16x16x32_bf16 v[56:59], v[172:175], v[184:187], v[56:59]
	v_mfma_f32_16x16x32_bf16 v[52:55], v[164:167], v[184:187], v[52:55]
	v_mfma_f32_16x16x32_bf16 v[48:51], v[160:163], v[184:187], v[48:51]
	ds_read_b128 v[184:187], v248 offset:43840
	ds_read_b128 v[248:251], v192 offset:64
	s_waitcnt lgkmcnt(5)
	v_mfma_f32_16x16x32_bf16 v[44:47], v[168:171], v[180:183], v[44:47]
	ds_read_b128 v[168:171], v192 offset:2368
	v_mfma_f32_16x16x32_bf16 v[40:43], v[172:175], v[180:183], v[40:43]
	ds_read_b128 v[172:175], v192 offset:4672
	v_mfma_f32_16x16x32_bf16 v[36:39], v[164:167], v[180:183], v[36:39]
	ds_read_b128 v[164:167], v192 offset:6976
	v_mfma_f32_16x16x32_bf16 v[32:35], v[160:163], v[180:183], v[32:35]
	ds_read_b128 v[160:163], v192 offset:9280
	ds_read_b128 v[180:183], v192 offset:11584
	s_waitcnt lgkmcnt(5)
	v_mfma_f32_16x16x32_bf16 v[156:159], v[176:179], v[248:251], v[156:159]
	v_mfma_f32_16x16x32_bf16 v[152:155], v[216:219], v[248:251], v[152:155]
	v_mfma_f32_16x16x32_bf16 v[148:151], v[188:191], v[248:251], v[148:151]
	v_mfma_f32_16x16x32_bf16 v[144:147], v[184:187], v[248:251], v[144:147]
	ds_read_b128 v[248:251], v192 offset:13888
	s_waitcnt lgkmcnt(5)
	v_mfma_f32_16x16x32_bf16 v[140:143], v[176:179], v[168:171], v[140:143]
	v_mfma_f32_16x16x32_bf16 v[136:139], v[216:219], v[168:171], v[136:139]
	v_mfma_f32_16x16x32_bf16 v[132:135], v[188:191], v[168:171], v[132:135]
	v_mfma_f32_16x16x32_bf16 v[128:131], v[184:187], v[168:171], v[128:131]
	ds_read_b128 v[168:171], v192 offset:16192
	s_waitcnt lgkmcnt(5)
	v_mfma_f32_16x16x32_bf16 v[124:127], v[176:179], v[172:175], v[124:127]
	v_mfma_f32_16x16x32_bf16 v[120:123], v[216:219], v[172:175], v[120:123]
	v_mfma_f32_16x16x32_bf16 v[116:119], v[188:191], v[172:175], v[116:119]
	v_mfma_f32_16x16x32_bf16 v[112:115], v[184:187], v[172:175], v[112:115]
	s_bitcmp1_b32 s25, 0
	s_cselect_b32 s1, 0x12000, 0
	v_or_b32_e32 v172, s1, v196
	v_add_u32_e32 v172, v172, v233
	s_waitcnt vmcnt(7)
	ds_write_b128 v172, v[0:3]
	s_waitcnt vmcnt(6)
	ds_write_b128 v172, v[4:7] offset:9216
	s_waitcnt lgkmcnt(6)
	v_mfma_f32_16x16x32_bf16 v[108:111], v[176:179], v[164:167], v[108:111]
	v_mfma_f32_16x16x32_bf16 v[104:107], v[216:219], v[164:167], v[104:107]
	v_mfma_f32_16x16x32_bf16 v[100:103], v[188:191], v[164:167], v[100:103]
	v_mfma_f32_16x16x32_bf16 v[96:99], v[184:187], v[164:167], v[96:99]
	s_waitcnt vmcnt(5)
	ds_write_b128 v172, v[8:11] offset:18432
	s_waitcnt vmcnt(4)
	ds_write_b128 v172, v[12:15] offset:27648
	s_waitcnt lgkmcnt(7)
	v_mfma_f32_16x16x32_bf16 v[92:95], v[176:179], v[160:163], v[92:95]
	v_mfma_f32_16x16x32_bf16 v[88:91], v[216:219], v[160:163], v[88:91]
	v_mfma_f32_16x16x32_bf16 v[84:87], v[188:191], v[160:163], v[84:87]
	v_mfma_f32_16x16x32_bf16 v[80:83], v[184:187], v[160:163], v[80:83]
	s_waitcnt vmcnt(3)
	ds_write_b128 v172, v[16:19] offset:36864
	s_waitcnt vmcnt(2)
	ds_write_b128 v172, v[20:23] offset:46080
	s_waitcnt lgkmcnt(8)
	v_mfma_f32_16x16x32_bf16 v[76:79], v[176:179], v[180:183], v[76:79]
	v_mfma_f32_16x16x32_bf16 v[72:75], v[216:219], v[180:183], v[72:75]
	v_mfma_f32_16x16x32_bf16 v[68:71], v[188:191], v[180:183], v[68:71]
	v_mfma_f32_16x16x32_bf16 v[64:67], v[184:187], v[180:183], v[64:67]
	s_waitcnt vmcnt(1)
	ds_write_b128 v172, v[24:27] offset:55296
	s_waitcnt vmcnt(0)
	ds_write_b128 v172, v[28:31] offset:64512

; #define MFMA16(a, b, c) __builtin_amdgcn_mfma_f32_16x16x32_bf16((a), (b), (c), 0, 0, 0)
;     ...
;       for (int gi = 0; gi < NG; ++gi) {
;         const int ks = gi / HG;
;         if (gi + 1 < NG) {
;           const int ks1 = (gi + 1) / HG, h1 = (gi + 1) % HG;
;           if (ks1 != ks) {
; #pragma unroll
;             for (int j = 0; j < 4; ++j) fb[ks1 & 1][j] = *(const bf16x8*)(pB + (j * 16) * LDSS + ks1 * 32);
;           }
; #pragma unroll
;           for (int i = 0; i < FA; ++i) fa[(gi + 1) & 1][i] = *(const bf16x8*)(pA + ((h1 * FA + i) * 16) * LDSS + ks1 * 32);
;         }
;         const int h = gi % HG;
; #pragma unroll
;         for (int i = 0; i < FA; ++i)
; #pragma unroll
;           for (int j = 0; j < 4; ++j)
;             acc[h * FA + i][j] = NAT ? MFMA16(fa[gi & 1][i], fb[ks & 1][j], acc[h * FA + i][j]) : MFMA16(fb[ks & 1][j], fa[gi & 1][i], acc[h * FA + i][j]);
;         __builtin_amdgcn_sched_barrier(0);
;       }
;     }
;     if (kt == nk - 1) {
.LBB0_534:
	s_waitcnt lgkmcnt(9)
	v_mfma_f32_16x16x32_bf16 v[60:63], v[176:179], v[248:251], v[60:63]
	v_mfma_f32_16x16x32_bf16 v[56:59], v[216:219], v[248:251], v[56:59]
	v_mfma_f32_16x16x32_bf16 v[52:55], v[188:191], v[248:251], v[52:55]
	v_mfma_f32_16x16x32_bf16 v[48:51], v[184:187], v[248:251], v[48:51]
	s_waitcnt lgkmcnt(8)
	v_mfma_f32_16x16x32_bf16 v[44:47], v[176:179], v[168:171], v[44:47]
	v_mfma_f32_16x16x32_bf16 v[40:43], v[216:219], v[168:171], v[40:43]
	v_mfma_f32_16x16x32_bf16 v[36:39], v[188:191], v[168:171], v[36:39]
	v_mfma_f32_16x16x32_bf16 v[32:35], v[184:187], v[168:171], v[32:35]
	s_waitcnt lgkmcnt(0)
	s_cmp_lg_u32 s30, 15
	s_mov_b64 s[0:1], -1
	s_cbranch_scc0 .LBB0_536
	s_add_i32 s30, s30, 1
	s_mov_b64 s[0:1], 0

; #define MFMA16(a, b, c) __builtin_amdgcn_mfma_f32_16x16x32_bf16((a), (b), (c), 0, 0, 0)
;     ...
;     bf16_t* sA = sm + (q & 1) * STG; bf16_t* sB = sA + BM * LDSS;
;     constexpr int FA = MI < 4 ? MI : 4, HG = MI / FA, NG = 2 * HG;
;     bf16x8 fb[2][4], fa[2][FA];
;     const bf16_t* pA = sA + (wm * MI * 16) * LDSS + fro; const bf16_t* pB = sB + (wn * 64) * LDSS + fro;
; #pragma unroll
;     for (int j = 0; j < 4; ++j) fb[0][j] = *(const bf16x8*)(pB + (j * 16) * LDSS);
; #pragma unroll
;     for (int i = 0; i < FA; ++i) fa[0][i] = *(const bf16x8*)(pA + (i * 16) * LDSS);
;     __builtin_amdgcn_sched_barrier(0);
;     if (q + 1 < Q) {
;       bf16_t* nA = sm + ((q + 1) & 1) * STG; bf16_t* nB = nA + BM * LDSS;
; #pragma unroll
;       for (int i = 0; i < AR; ++i) *(u32x4*)(nA + (lr + 64 * i) * LDSS + lc) = ra[i];
; #pragma unroll
;       for (int i = 0; i < BR; ++i) *(u32x4*)(nB + (lr + 64 * i) * LDSS + lc) = rb[i];
;     }
;     if (q + 2 < Q) {
;       int kt2 = kt + 2;
;       if (kt2 >= nk) { kt2 -= nk; if (kt2 == 0) set_offs(jt + 1); }
;       const char* gk = gb + kt2 * 128;
; #pragma unroll
;       for (int i = 0; i < AR; ++i) ra[i] = *(const u32x4*)(gk + ap[i]);
; #pragma unroll
;       for (int i = 0; i < BR; ++i) rb[i] = *(const u32x4*)(gk + bp[i]);
;     }
;     __builtin_amdgcn_sched_barrier(0);
;     {
; #pragma unroll
;       for (int gi = 0; gi < NG; ++gi) {
;         const int ks = gi / HG;
;         if (gi + 1 < NG) {
;           const int ks1 = (gi + 1) / HG, h1 = (gi + 1) % HG;
;           if (ks1 != ks) {
; #pragma unroll
;             for (int j = 0; j < 4; ++j) fb[ks1 & 1][j] = *(const bf16x8*)(pB + (j * 16) * LDSS + ks1 * 32);
;           }
; #pragma unroll
;           for (int i = 0; i < FA; ++i) fa[(gi + 1) & 1][i] = *(const bf16x8*)(pA + ((h1 * FA + i) * 16) * LDSS + ks1 * 32);
;         }
;         const int h = gi % HG;
; #pragma unroll
;         for (int i = 0; i < FA; ++i)
; #pragma unroll
;           for (int j = 0; j < 4; ++j)
;             acc[h * FA + i][j] = NAT ? MFMA16(fa[gi & 1][i], fb[ks & 1][j], acc[h * FA + i][j]) : MFMA16(fb[ks & 1][j], fa[gi & 1][i], acc[h * FA + i][j]);
;         __builtin_amdgcn_sched_barrier(0);
.LBB0_593:
	s_bitcmp1_b32 s0, 0
	s_cselect_b32 s1, 0x12000, 0
	v_add3_u32 v245, s1, v240, v235
	v_add3_u32 v244, s1, v237, v235
	ds_read_b128 v[168:171], v245 offset:36864
	ds_read_b128 v[188:191], v244
	ds_read_b128 v[172:175], v245 offset:39168
	ds_read_b128 v[164:167], v245 offset:41472
	ds_read_b128 v[160:163], v245 offset:43776
	ds_read_b128 v[184:187], v244 offset:2304
	ds_read_b128 v[180:183], v244 offset:4608
	ds_read_b128 v[176:179], v244 offset:6912
	s_add_i32 s30, s0, 1
	s_waitcnt lgkmcnt(6)
	v_mfma_f32_16x16x32_bf16 v[156:159], v[188:191], v[168:171], v[156:159]
	s_waitcnt lgkmcnt(5)
	v_mfma_f32_16x16x32_bf16 v[152:155], v[188:191], v[172:175], v[152:155]
	s_waitcnt lgkmcnt(4)
	v_mfma_f32_16x16x32_bf16 v[148:151], v[188:191], v[164:167], v[148:151]
	s_waitcnt lgkmcnt(3)
	v_mfma_f32_16x16x32_bf16 v[144:147], v[188:191], v[160:163], v[144:147]
	ds_read_b128 v[216:219], v244 offset:9216
	ds_read_b128 v[188:191], v244 offset:11520
	s_waitcnt lgkmcnt(4)
	v_mfma_f32_16x16x32_bf16 v[140:143], v[184:187], v[168:171], v[140:143]
	v_mfma_f32_16x16x32_bf16 v[136:139], v[184:187], v[172:175], v[136:139]
	v_mfma_f32_16x16x32_bf16 v[132:135], v[184:187], v[164:167], v[132:135]
	v_mfma_f32_16x16x32_bf16 v[128:131], v[184:187], v[160:163], v[128:131]
	ds_read_b128 v[184:187], v244 offset:13824
	s_waitcnt lgkmcnt(4)
	v_mfma_f32_16x16x32_bf16 v[124:127], v[180:183], v[168:171], v[124:127]
	v_mfma_f32_16x16x32_bf16 v[120:123], v[180:183], v[172:175], v[120:123]
	v_mfma_f32_16x16x32_bf16 v[116:119], v[180:183], v[164:167], v[116:119]
	v_mfma_f32_16x16x32_bf16 v[112:115], v[180:183], v[160:163], v[112:115]
	ds_read_b128 v[180:183], v244 offset:16128
	s_waitcnt lgkmcnt(4)
	v_mfma_f32_16x16x32_bf16 v[108:111], v[176:179], v[168:171], v[108:111]
	v_mfma_f32_16x16x32_bf16 v[104:107], v[176:179], v[172:175], v[104:107]
	v_mfma_f32_16x16x32_bf16 v[100:103], v[176:179], v[164:167], v[100:103]
	v_mfma_f32_16x16x32_bf16 v[96:99], v[176:179], v[160:163], v[96:99]
	ds_read_b128 v[176:179], v245 offset:36928
	s_waitcnt lgkmcnt(4)
	v_mfma_f32_16x16x32_bf16 v[92:95], v[216:219], v[168:171], v[92:95]
	v_mfma_f32_16x16x32_bf16 v[88:91], v[216:219], v[172:175], v[88:91]
	v_mfma_f32_16x16x32_bf16 v[84:87], v[216:219], v[164:167], v[84:87]
	v_mfma_f32_16x16x32_bf16 v[80:83], v[216:219], v[160:163], v[80:83]
	ds_read_b128 v[216:219], v245 offset:39232
	s_waitcnt lgkmcnt(4)
	v_mfma_f32_16x16x32_bf16 v[76:79], v[188:191], v[168:171], v[76:79]
	v_mfma_f32_16x16x32_bf16 v[72:75], v[188:191], v[172:175], v[72:75]
	v_mfma_f32_16x16x32_bf16 v[68:71], v[188:191], v[164:167], v[68:71]
	v_mfma_f32_16x16x32_bf16 v[64:67], v[188:191], v[160:163], v[64:67]
	ds_read_b128 v[188:191], v245 offset:41536
	s_waitcnt lgkmcnt(4)
	v_mfma_f32_16x16x32_bf16 v[60:63], v[184:187], v[168:171], v[60:63]
	v_mfma_f32_16x16x32_bf16 v[56:59], v[184:187], v[172:175], v[56:59]
	v_mfma_f32_16x16x32_bf16 v[52:55], v[184:187], v[164:167], v[52:55]
	v_mfma_f32_16x16x32_bf16 v[48:51], v[184:187], v[160:163], v[48:51]
	ds_read_b128 v[184:187], v245 offset:43840
	ds_read_b128 v[246:249], v244 offset:64
	s_waitcnt lgkmcnt(5)
	v_mfma_f32_16x16x32_bf16 v[44:47], v[180:183], v[168:171], v[44:47]
	ds_read_b128 v[168:171], v244 offset:2368
	v_mfma_f32_16x16x32_bf16 v[40:43], v[180:183], v[172:175], v[40:43]
	ds_read_b128 v[172:175], v244 offset:4672
	v_mfma_f32_16x16x32_bf16 v[36:39], v[180:183], v[164:167], v[36:39]
	ds_read_b128 v[164:167], v244 offset:6976
	v_mfma_f32_16x16x32_bf16 v[8:11], v[180:183], v[160:163], v[8:11]
	ds_read_b128 v[160:163], v244 offset:9280
	ds_read_b128 v[180:183], v244 offset:11584
	s_waitcnt lgkmcnt(5)
	v_mfma_f32_16x16x32_bf16 v[156:159], v[246:249], v[176:179], v[156:159]
	v_mfma_f32_16x16x32_bf16 v[152:155], v[246:249], v[216:219], v[152:155]
	v_mfma_f32_16x16x32_bf16 v[148:151], v[246:249], v[188:191], v[148:151]
	v_mfma_f32_16x16x32_bf16 v[144:147], v[246:249], v[184:187], v[144:147]
	ds_read_b128 v[246:249], v244 offset:13888
	s_waitcnt lgkmcnt(5)
	v_mfma_f32_16x16x32_bf16 v[140:143], v[168:171], v[176:179], v[140:143]
	v_mfma_f32_16x16x32_bf16 v[136:139], v[168:171], v[216:219], v[136:139]
	v_mfma_f32_16x16x32_bf16 v[132:135], v[168:171], v[188:191], v[132:135]
	v_mfma_f32_16x16x32_bf16 v[128:131], v[168:171], v[184:187], v[128:131]
	ds_read_b128 v[168:171], v244 offset:16192
	s_waitcnt lgkmcnt(5)
	v_mfma_f32_16x16x32_bf16 v[124:127], v[172:175], v[176:179], v[124:127]
	v_mfma_f32_16x16x32_bf16 v[120:123], v[172:175], v[216:219], v[120:123]
	v_mfma_f32_16x16x32_bf16 v[116:119], v[172:175], v[188:191], v[116:119]
	v_mfma_f32_16x16x32_bf16 v[112:115], v[172:175], v[184:187], v[112:115]
	s_bitcmp1_b32 s30, 0
	s_cselect_b32 s1, 0x12000, 0
	v_or_b32_e32 v172, s1, v194
	v_add_u32_e32 v172, v172, v234
	s_waitcnt vmcnt(7)
	ds_write_b128 v172, v[0:3]
	s_waitcnt vmcnt(6)
	ds_write_b128 v172, v[4:7] offset:9216
	s_waitcnt lgkmcnt(6)
	v_mfma_f32_16x16x32_bf16 v[108:111], v[164:167], v[176:179], v[108:111]
	v_mfma_f32_16x16x32_bf16 v[104:107], v[164:167], v[216:219], v[104:107]
	v_mfma_f32_16x16x32_bf16 v[100:103], v[164:167], v[188:191], v[100:103]
	v_mfma_f32_16x16x32_bf16 v[96:99], v[164:167], v[184:187], v[96:99]
	s_waitcnt vmcnt(5)
	ds_write_b128 v172, v[12:15] offset:18432
	s_waitcnt vmcnt(4)
	ds_write_b128 v172, v[16:19] offset:27648
	s_waitcnt lgkmcnt(7)
	v_mfma_f32_16x16x32_bf16 v[92:95], v[160:163], v[176:179], v[92:95]
	v_mfma_f32_16x16x32_bf16 v[88:91], v[160:163], v[216:219], v[88:91]
	v_mfma_f32_16x16x32_bf16 v[84:87], v[160:163], v[188:191], v[84:87]
	v_mfma_f32_16x16x32_bf16 v[80:83], v[160:163], v[184:187], v[80:83]
	s_waitcnt vmcnt(3)
	ds_write_b128 v172, v[20:23] offset:36864
	s_waitcnt vmcnt(2)
	ds_write_b128 v172, v[24:27] offset:46080
	s_waitcnt lgkmcnt(8)
	v_mfma_f32_16x16x32_bf16 v[76:79], v[180:183], v[176:179], v[76:79]
	v_mfma_f32_16x16x32_bf16 v[72:75], v[180:183], v[216:219], v[72:75]
	v_mfma_f32_16x16x32_bf16 v[68:71], v[180:183], v[188:191], v[68:71]
	v_mfma_f32_16x16x32_bf16 v[64:67], v[180:183], v[184:187], v[64:67]
	s_waitcnt vmcnt(1)
	ds_write_b128 v172, v[28:31] offset:55296
	s_waitcnt vmcnt(0)
	ds_write_b128 v172, v[32:35] offset:64512

; #define MFMA16(a, b, c) __builtin_amdgcn_mfma_f32_16x16x32_bf16((a), (b), (c), 0, 0, 0)
;     ...
;       for (int gi = 0; gi < NG; ++gi) {
;         const int ks = gi / HG;
;         if (gi + 1 < NG) {
;           const int ks1 = (gi + 1) / HG, h1 = (gi + 1) % HG;
;           if (ks1 != ks) {
; #pragma unroll
;             for (int j = 0; j < 4; ++j) fb[ks1 & 1][j] = *(const bf16x8*)(pB + (j * 16) * LDSS + ks1 * 32);
;           }
; #pragma unroll
;           for (int i = 0; i < FA; ++i) fa[(gi + 1) & 1][i] = *(const bf16x8*)(pA + ((h1 * FA + i) * 16) * LDSS + ks1 * 32);
;         }
;         const int h = gi % HG;
; #pragma unroll
;         for (int i = 0; i < FA; ++i)
; #pragma unroll
;           for (int j = 0; j < 4; ++j)
;             acc[h * FA + i][j] = NAT ? MFMA16(fa[gi & 1][i], fb[ks & 1][j], acc[h * FA + i][j]) : MFMA16(fb[ks & 1][j], fa[gi & 1][i], acc[h * FA + i][j]);
;         __builtin_amdgcn_sched_barrier(0);
;       }
;     }
;     if (kt == nk - 1) {
.LBB0_605:
	s_waitcnt lgkmcnt(9)
	v_mfma_f32_16x16x32_bf16 v[60:63], v[246:249], v[176:179], v[60:63]
	v_mfma_f32_16x16x32_bf16 v[56:59], v[246:249], v[216:219], v[56:59]
	v_mfma_f32_16x16x32_bf16 v[52:55], v[246:249], v[188:191], v[52:55]
	v_mfma_f32_16x16x32_bf16 v[48:51], v[246:249], v[184:187], v[48:51]
	s_waitcnt lgkmcnt(8)
	v_mfma_f32_16x16x32_bf16 v[44:47], v[168:171], v[176:179], v[44:47]
	v_mfma_f32_16x16x32_bf16 v[40:43], v[168:171], v[216:219], v[40:43]
	v_mfma_f32_16x16x32_bf16 v[36:39], v[168:171], v[188:191], v[36:39]
	v_mfma_f32_16x16x32_bf16 v[8:11], v[168:171], v[184:187], v[8:11]
	s_waitcnt lgkmcnt(0)
	s_cmp_lg_u32 s25, 15
	s_mov_b64 s[0:1], -1
	s_cbranch_scc0 .LBB0_607
	s_add_i32 s25, s25, 1
	s_mov_b64 s[0:1], 0

; #define MFMA16(a, b, c) __builtin_amdgcn_mfma_f32_16x16x32_bf16((a), (b), (c), 0, 0, 0)
;     ...
;     bf16_t* sA = sm + (q & 1) * STG; bf16_t* sB = sA + BM * LDSS;
;     constexpr int FA = MI < 4 ? MI : 4, HG = MI / FA, NG = 2 * HG;
;     bf16x8 fb[2][4], fa[2][FA];
;     const bf16_t* pA = sA + (wm * MI * 16) * LDSS + fro; const bf16_t* pB = sB + (wn * 64) * LDSS + fro;
; #pragma unroll
;     for (int j = 0; j < 4; ++j) fb[0][j] = *(const bf16x8*)(pB + (j * 16) * LDSS);
; #pragma unroll
;     for (int i = 0; i < FA; ++i) fa[0][i] = *(const bf16x8*)(pA + (i * 16) * LDSS);
;     __builtin_amdgcn_sched_barrier(0);
;     if (q + 1 < Q) {
;       bf16_t* nA = sm + ((q + 1) & 1) * STG; bf16_t* nB = nA + BM * LDSS;
; #pragma unroll
;       for (int i = 0; i < AR; ++i) *(u32x4*)(nA + (lr + 64 * i) * LDSS + lc) = ra[i];
; #pragma unroll
;       for (int i = 0; i < BR; ++i) *(u32x4*)(nB + (lr + 64 * i) * LDSS + lc) = rb[i];
;     }
;     if (q + 2 < Q) {
;       int kt2 = kt + 2;
;       if (kt2 >= nk) { kt2 -= nk; if (kt2 == 0) set_offs(jt + 1); }
;       const char* gk = gb + kt2 * 128;
; #pragma unroll
;       for (int i = 0; i < AR; ++i) ra[i] = *(const u32x4*)(gk + ap[i]);
; #pragma unroll
;       for (int i = 0; i < BR; ++i) rb[i] = *(const u32x4*)(gk + bp[i]);
;     }
;     __builtin_amdgcn_sched_barrier(0);
;     {
; #pragma unroll
;       for (int gi = 0; gi < NG; ++gi) {
;         const int ks = gi / HG;
;         if (gi + 1 < NG) {
;           const int ks1 = (gi + 1) / HG, h1 = (gi + 1) % HG;
;           if (ks1 != ks) {
; #pragma unroll
;             for (int j = 0; j < 4; ++j) fb[ks1 & 1][j] = *(const bf16x8*)(pB + (j * 16) * LDSS + ks1 * 32);
;           }
; #pragma unroll
;           for (int i = 0; i < FA; ++i) fa[(gi + 1) & 1][i] = *(const bf16x8*)(pA + ((h1 * FA + i) * 16) * LDSS + ks1 * 32);
;         }
;         const int h = gi % HG;
; #pragma unroll
;         for (int i = 0; i < FA; ++i)
; #pragma unroll
;           for (int j = 0; j < 4; ++j)
;             acc[h * FA + i][j] = NAT ? MFMA16(fa[gi & 1][i], fb[ks & 1][j], acc[h * FA + i][j]) : MFMA16(fb[ks & 1][j], fa[gi & 1][i], acc[h * FA + i][j]);
;         __builtin_amdgcn_sched_barrier(0);
.LBB0_1008:
	s_bitcmp1_b32 s0, 0
	s_cselect_b32 s1, 0x12000, 0
	v_add3_u32 v248, s1, v242, v246
	v_add3_u32 v247, s1, v241, v246
	ds_read_b128 v[168:171], v248 offset:36864
	ds_read_b128 v[188:191], v247
	ds_read_b128 v[172:175], v248 offset:39168
	ds_read_b128 v[164:167], v248 offset:41472
	ds_read_b128 v[160:163], v248 offset:43776
	ds_read_b128 v[184:187], v247 offset:2304
	ds_read_b128 v[180:183], v247 offset:4608
	ds_read_b128 v[176:179], v247 offset:6912
	s_add_i32 s30, s0, 1
	s_waitcnt lgkmcnt(6)
	v_mfma_f32_16x16x32_bf16 v[156:159], v[168:171], v[188:191], v[156:159]
	s_waitcnt lgkmcnt(5)
	v_mfma_f32_16x16x32_bf16 v[152:155], v[172:175], v[188:191], v[152:155]
	s_waitcnt lgkmcnt(4)
	v_mfma_f32_16x16x32_bf16 v[148:151], v[164:167], v[188:191], v[148:151]
	s_waitcnt lgkmcnt(3)
	v_mfma_f32_16x16x32_bf16 v[144:147], v[160:163], v[188:191], v[144:147]
	ds_read_b128 v[216:219], v247 offset:9216
	ds_read_b128 v[188:191], v247 offset:11520
	s_waitcnt lgkmcnt(4)
	v_mfma_f32_16x16x32_bf16 v[140:143], v[168:171], v[184:187], v[140:143]
	v_mfma_f32_16x16x32_bf16 v[136:139], v[172:175], v[184:187], v[136:139]
	v_mfma_f32_16x16x32_bf16 v[132:135], v[164:167], v[184:187], v[132:135]
	v_mfma_f32_16x16x32_bf16 v[128:131], v[160:163], v[184:187], v[128:131]
	ds_read_b128 v[184:187], v247 offset:13824
	s_waitcnt lgkmcnt(4)
	v_mfma_f32_16x16x32_bf16 v[124:127], v[168:171], v[180:183], v[124:127]
	v_mfma_f32_16x16x32_bf16 v[120:123], v[172:175], v[180:183], v[120:123]
	v_mfma_f32_16x16x32_bf16 v[116:119], v[164:167], v[180:183], v[116:119]
	v_mfma_f32_16x16x32_bf16 v[112:115], v[160:163], v[180:183], v[112:115]
	ds_read_b128 v[180:183], v247 offset:16128
	s_waitcnt lgkmcnt(4)
	v_mfma_f32_16x16x32_bf16 v[108:111], v[168:171], v[176:179], v[108:111]
	v_mfma_f32_16x16x32_bf16 v[104:107], v[172:175], v[176:179], v[104:107]
	v_mfma_f32_16x16x32_bf16 v[100:103], v[164:167], v[176:179], v[100:103]
	v_mfma_f32_16x16x32_bf16 v[96:99], v[160:163], v[176:179], v[96:99]
	ds_read_b128 v[176:179], v248 offset:36928
	s_waitcnt lgkmcnt(4)
	v_mfma_f32_16x16x32_bf16 v[92:95], v[168:171], v[216:219], v[92:95]
	v_mfma_f32_16x16x32_bf16 v[88:91], v[172:175], v[216:219], v[88:91]
	v_mfma_f32_16x16x32_bf16 v[84:87], v[164:167], v[216:219], v[84:87]
	v_mfma_f32_16x16x32_bf16 v[80:83], v[160:163], v[216:219], v[80:83]
	ds_read_b128 v[216:219], v248 offset:39232
	s_waitcnt lgkmcnt(4)
	v_mfma_f32_16x16x32_bf16 v[76:79], v[168:171], v[188:191], v[76:79]
	v_mfma_f32_16x16x32_bf16 v[72:75], v[172:175], v[188:191], v[72:75]
	v_mfma_f32_16x16x32_bf16 v[68:71], v[164:167], v[188:191], v[68:71]
	v_mfma_f32_16x16x32_bf16 v[64:67], v[160:163], v[188:191], v[64:67]
	ds_read_b128 v[188:191], v248 offset:41536
	s_waitcnt lgkmcnt(4)
	v_mfma_f32_16x16x32_bf16 v[60:63], v[168:171], v[184:187], v[60:63]
	v_mfma_f32_16x16x32_bf16 v[56:59], v[172:175], v[184:187], v[56:59]
	v_mfma_f32_16x16x32_bf16 v[52:55], v[164:167], v[184:187], v[52:55]
	v_mfma_f32_16x16x32_bf16 v[48:51], v[160:163], v[184:187], v[48:51]
	ds_read_b128 v[184:187], v248 offset:43840
	ds_read_b128 v[248:251], v247 offset:64
	s_waitcnt lgkmcnt(5)
	v_mfma_f32_16x16x32_bf16 v[44:47], v[168:171], v[180:183], v[44:47]
	ds_read_b128 v[168:171], v247 offset:2368
	v_mfma_f32_16x16x32_bf16 v[40:43], v[172:175], v[180:183], v[40:43]
	ds_read_b128 v[172:175], v247 offset:4672
	v_mfma_f32_16x16x32_bf16 v[36:39], v[164:167], v[180:183], v[36:39]
	ds_read_b128 v[164:167], v247 offset:6976
	v_mfma_f32_16x16x32_bf16 v[32:35], v[160:163], v[180:183], v[32:35]
	ds_read_b128 v[160:163], v247 offset:9280
	ds_read_b128 v[180:183], v247 offset:11584
	s_waitcnt lgkmcnt(5)
	v_mfma_f32_16x16x32_bf16 v[156:159], v[176:179], v[248:251], v[156:159]
	v_mfma_f32_16x16x32_bf16 v[152:155], v[216:219], v[248:251], v[152:155]
	v_mfma_f32_16x16x32_bf16 v[148:151], v[188:191], v[248:251], v[148:151]
	v_mfma_f32_16x16x32_bf16 v[144:147], v[184:187], v[248:251], v[144:147]
	ds_read_b128 v[248:251], v247 offset:13888
	s_waitcnt lgkmcnt(5)
	v_mfma_f32_16x16x32_bf16 v[140:143], v[176:179], v[168:171], v[140:143]
	v_mfma_f32_16x16x32_bf16 v[136:139], v[216:219], v[168:171], v[136:139]
	v_mfma_f32_16x16x32_bf16 v[132:135], v[188:191], v[168:171], v[132:135]
	v_mfma_f32_16x16x32_bf16 v[128:131], v[184:187], v[168:171], v[128:131]
	ds_read_b128 v[168:171], v247 offset:16192
	s_waitcnt lgkmcnt(5)
	v_mfma_f32_16x16x32_bf16 v[124:127], v[176:179], v[172:175], v[124:127]
	v_mfma_f32_16x16x32_bf16 v[120:123], v[216:219], v[172:175], v[120:123]
	v_mfma_f32_16x16x32_bf16 v[116:119], v[188:191], v[172:175], v[116:119]
	v_mfma_f32_16x16x32_bf16 v[112:115], v[184:187], v[172:175], v[112:115]
	s_bitcmp1_b32 s30, 0
	s_cselect_b32 s1, 0x12000, 0
	v_or_b32_e32 v172, s1, v192
	v_add_u32_e32 v172, v172, v239
	s_waitcnt vmcnt(7)
	ds_write_b128 v172, v[0:3]
	s_waitcnt vmcnt(6)
	ds_write_b128 v172, v[4:7] offset:9216
	s_waitcnt lgkmcnt(6)
	v_mfma_f32_16x16x32_bf16 v[108:111], v[176:179], v[164:167], v[108:111]
	v_mfma_f32_16x16x32_bf16 v[104:107], v[216:219], v[164:167], v[104:107]
	v_mfma_f32_16x16x32_bf16 v[100:103], v[188:191], v[164:167], v[100:103]
	v_mfma_f32_16x16x32_bf16 v[96:99], v[184:187], v[164:167], v[96:99]
	s_waitcnt vmcnt(5)
	ds_write_b128 v172, v[8:11] offset:18432
	s_waitcnt vmcnt(4)
	ds_write_b128 v172, v[12:15] offset:27648
	s_waitcnt lgkmcnt(7)
	v_mfma_f32_16x16x32_bf16 v[92:95], v[176:179], v[160:163], v[92:95]
	v_mfma_f32_16x16x32_bf16 v[88:91], v[216:219], v[160:163], v[88:91]
	v_mfma_f32_16x16x32_bf16 v[84:87], v[188:191], v[160:163], v[84:87]
	v_mfma_f32_16x16x32_bf16 v[80:83], v[184:187], v[160:163], v[80:83]
	s_waitcnt vmcnt(3)
	ds_write_b128 v172, v[16:19] offset:36864
	s_waitcnt vmcnt(2)
	ds_write_b128 v172, v[20:23] offset:46080
	s_waitcnt lgkmcnt(8)
	v_mfma_f32_16x16x32_bf16 v[76:79], v[176:179], v[180:183], v[76:79]
	v_mfma_f32_16x16x32_bf16 v[72:75], v[216:219], v[180:183], v[72:75]
	v_mfma_f32_16x16x32_bf16 v[68:71], v[188:191], v[180:183], v[68:71]
	v_mfma_f32_16x16x32_bf16 v[64:67], v[184:187], v[180:183], v[64:67]
	s_waitcnt vmcnt(1)
	ds_write_b128 v172, v[24:27] offset:55296
	s_waitcnt vmcnt(0)
	ds_write_b128 v172, v[28:31] offset:64512

; #define MFMA16(a, b, c) __builtin_amdgcn_mfma_f32_16x16x32_bf16((a), (b), (c), 0, 0, 0)
;     ...
;       for (int gi = 0; gi < NG; ++gi) {
;         const int ks = gi / HG;
;         if (gi + 1 < NG) {
;           const int ks1 = (gi + 1) / HG, h1 = (gi + 1) % HG;
;           if (ks1 != ks) {
; #pragma unroll
;             for (int j = 0; j < 4; ++j) fb[ks1 & 1][j] = *(const bf16x8*)(pB + (j * 16) * LDSS + ks1 * 32);
;           }
; #pragma unroll
;           for (int i = 0; i < FA; ++i) fa[(gi + 1) & 1][i] = *(const bf16x8*)(pA + ((h1 * FA + i) * 16) * LDSS + ks1 * 32);
;         }
;         const int h = gi % HG;
; #pragma unroll
;         for (int i = 0; i < FA; ++i)
; #pragma unroll
;           for (int j = 0; j < 4; ++j)
;             acc[h * FA + i][j] = NAT ? MFMA16(fa[gi & 1][i], fb[ks & 1][j], acc[h * FA + i][j]) : MFMA16(fb[ks & 1][j], fa[gi & 1][i], acc[h * FA + i][j]);
;         __builtin_amdgcn_sched_barrier(0);
;       }
;     }
;     if (kt == nk - 1) {
.LBB0_1018:
	s_waitcnt lgkmcnt(9)
	v_mfma_f32_16x16x32_bf16 v[60:63], v[176:179], v[248:251], v[60:63]
	v_mfma_f32_16x16x32_bf16 v[56:59], v[216:219], v[248:251], v[56:59]
	v_mfma_f32_16x16x32_bf16 v[52:55], v[188:191], v[248:251], v[52:55]
	v_mfma_f32_16x16x32_bf16 v[48:51], v[184:187], v[248:251], v[48:51]
	s_waitcnt lgkmcnt(8)
	v_mfma_f32_16x16x32_bf16 v[44:47], v[176:179], v[168:171], v[44:47]
	v_mfma_f32_16x16x32_bf16 v[40:43], v[216:219], v[168:171], v[40:43]
	v_mfma_f32_16x16x32_bf16 v[36:39], v[188:191], v[168:171], v[36:39]
	v_mfma_f32_16x16x32_bf16 v[32:35], v[184:187], v[168:171], v[32:35]
	s_waitcnt lgkmcnt(0)
	s_cmp_lg_u32 s31, 15
	s_mov_b64 s[0:1], -1
	s_cbranch_scc0 .LBB0_1020
	s_add_i32 s31, s31, 1
	s_mov_b64 s[0:1], 0

; #define MFMA16(a, b, c) __builtin_amdgcn_mfma_f32_16x16x32_bf16((a), (b), (c), 0, 0, 0)
;     ...
;     bf16_t* sA = sm + (q & 1) * STG; bf16_t* sB = sA + BM * LDSS;
;     constexpr int FA = MI < 4 ? MI : 4, HG = MI / FA, NG = 2 * HG;
;     bf16x8 fb[2][4], fa[2][FA];
;     const bf16_t* pA = sA + (wm * MI * 16) * LDSS + fro; const bf16_t* pB = sB + (wn * 64) * LDSS + fro;
; #pragma unroll
;     for (int j = 0; j < 4; ++j) fb[0][j] = *(const bf16x8*)(pB + (j * 16) * LDSS);
; #pragma unroll
;     for (int i = 0; i < FA; ++i) fa[0][i] = *(const bf16x8*)(pA + (i * 16) * LDSS);
;     __builtin_amdgcn_sched_barrier(0);
;     if (q + 1 < Q) {
;       bf16_t* nA = sm + ((q + 1) & 1) * STG; bf16_t* nB = nA + BM * LDSS;
; #pragma unroll
;       for (int i = 0; i < AR; ++i) *(u32x4*)(nA + (lr + 64 * i) * LDSS + lc) = ra[i];
; #pragma unroll
;       for (int i = 0; i < BR; ++i) *(u32x4*)(nB + (lr + 64 * i) * LDSS + lc) = rb[i];
;     }
;     if (q + 2 < Q) {
;       int kt2 = kt + 2;
;       if (kt2 >= nk) { kt2 -= nk; if (kt2 == 0) set_offs(jt + 1); }
;       const char* gk = gb + kt2 * 128;
; #pragma unroll
;       for (int i = 0; i < AR; ++i) ra[i] = *(const u32x4*)(gk + ap[i]);
; #pragma unroll
;       for (int i = 0; i < BR; ++i) rb[i] = *(const u32x4*)(gk + bp[i]);
;     }
;     __builtin_amdgcn_sched_barrier(0);
;     {
; #pragma unroll
;       for (int gi = 0; gi < NG; ++gi) {
;         const int ks = gi / HG;
;         if (gi + 1 < NG) {
;           const int ks1 = (gi + 1) / HG, h1 = (gi + 1) % HG;
;           if (ks1 != ks) {
; #pragma unroll
;             for (int j = 0; j < 4; ++j) fb[ks1 & 1][j] = *(const bf16x8*)(pB + (j * 16) * LDSS + ks1 * 32);
;           }
; #pragma unroll
;           for (int i = 0; i < FA; ++i) fa[(gi + 1) & 1][i] = *(const bf16x8*)(pA + ((h1 * FA + i) * 16) * LDSS + ks1 * 32);
;         }
;         const int h = gi % HG;
; #pragma unroll
;         for (int i = 0; i < FA; ++i)
; #pragma unroll
;           for (int j = 0; j < 4; ++j)
;             acc[h * FA + i][j] = NAT ? MFMA16(fa[gi & 1][i], fb[ks & 1][j], acc[h * FA + i][j]) : MFMA16(fb[ks & 1][j], fa[gi & 1][i], acc[h * FA + i][j]);
;         __builtin_amdgcn_sched_barrier(0);
.LBB0_1276:
	s_bitcmp1_b32 s0, 0
	s_cselect_b32 s1, 0x12000, 0
	v_add3_u32 v248, s1, v244, v247
	v_add3_u32 v192, s1, v243, v247
	ds_read_b128 v[168:171], v248 offset:36864
	ds_read_b128 v[188:191], v192
	ds_read_b128 v[172:175], v248 offset:39168
	ds_read_b128 v[164:167], v248 offset:41472
	ds_read_b128 v[160:163], v248 offset:43776
	ds_read_b128 v[184:187], v192 offset:2304
	ds_read_b128 v[180:183], v192 offset:4608
	ds_read_b128 v[176:179], v192 offset:6912
	s_add_i32 s52, s0, 1
	s_waitcnt lgkmcnt(6)
	v_mfma_f32_16x16x32_bf16 v[156:159], v[168:171], v[188:191], v[156:159]
	s_waitcnt lgkmcnt(5)
	v_mfma_f32_16x16x32_bf16 v[152:155], v[172:175], v[188:191], v[152:155]
	s_waitcnt lgkmcnt(4)
	v_mfma_f32_16x16x32_bf16 v[92:95], v[164:167], v[188:191], v[92:95]
	s_waitcnt lgkmcnt(3)
	v_mfma_f32_16x16x32_bf16 v[88:91], v[160:163], v[188:191], v[88:91]
	ds_read_b128 v[216:219], v192 offset:9216
	ds_read_b128 v[188:191], v192 offset:11520
	s_waitcnt lgkmcnt(4)
	v_mfma_f32_16x16x32_bf16 v[148:151], v[168:171], v[184:187], v[148:151]
	v_mfma_f32_16x16x32_bf16 v[144:147], v[172:175], v[184:187], v[144:147]
	v_mfma_f32_16x16x32_bf16 v[84:87], v[164:167], v[184:187], v[84:87]
	v_mfma_f32_16x16x32_bf16 v[80:83], v[160:163], v[184:187], v[80:83]
	ds_read_b128 v[184:187], v192 offset:13824
	s_waitcnt lgkmcnt(4)
	v_mfma_f32_16x16x32_bf16 v[140:143], v[168:171], v[180:183], v[140:143]
	v_mfma_f32_16x16x32_bf16 v[136:139], v[172:175], v[180:183], v[136:139]
	v_mfma_f32_16x16x32_bf16 v[76:79], v[164:167], v[180:183], v[76:79]
	v_mfma_f32_16x16x32_bf16 v[72:75], v[160:163], v[180:183], v[72:75]
	ds_read_b128 v[180:183], v192 offset:16128
	s_waitcnt lgkmcnt(4)
	v_mfma_f32_16x16x32_bf16 v[132:135], v[168:171], v[176:179], v[132:135]
	v_mfma_f32_16x16x32_bf16 v[128:131], v[172:175], v[176:179], v[128:131]
	v_mfma_f32_16x16x32_bf16 v[68:71], v[164:167], v[176:179], v[68:71]
	v_mfma_f32_16x16x32_bf16 v[64:67], v[160:163], v[176:179], v[64:67]
	ds_read_b128 v[176:179], v248 offset:36928
	s_waitcnt lgkmcnt(4)
	v_mfma_f32_16x16x32_bf16 v[124:127], v[168:171], v[216:219], v[124:127]
	v_mfma_f32_16x16x32_bf16 v[120:123], v[172:175], v[216:219], v[120:123]
	v_mfma_f32_16x16x32_bf16 v[60:63], v[164:167], v[216:219], v[60:63]
	v_mfma_f32_16x16x32_bf16 v[56:59], v[160:163], v[216:219], v[56:59]
	ds_read_b128 v[216:219], v248 offset:39232
	s_waitcnt lgkmcnt(4)
	v_mfma_f32_16x16x32_bf16 v[116:119], v[168:171], v[188:191], v[116:119]
	v_mfma_f32_16x16x32_bf16 v[112:115], v[172:175], v[188:191], v[112:115]
	v_mfma_f32_16x16x32_bf16 v[52:55], v[164:167], v[188:191], v[52:55]
	v_mfma_f32_16x16x32_bf16 v[48:51], v[160:163], v[188:191], v[48:51]
	ds_read_b128 v[188:191], v248 offset:41536
	s_waitcnt lgkmcnt(4)
	v_mfma_f32_16x16x32_bf16 v[108:111], v[168:171], v[184:187], v[108:111]
	v_mfma_f32_16x16x32_bf16 v[104:107], v[172:175], v[184:187], v[104:107]
	v_mfma_f32_16x16x32_bf16 v[44:47], v[164:167], v[184:187], v[44:47]
	v_mfma_f32_16x16x32_bf16 v[40:43], v[160:163], v[184:187], v[40:43]
	ds_read_b128 v[184:187], v248 offset:43840
	ds_read_b128 v[248:251], v192 offset:64
	s_waitcnt lgkmcnt(5)
	v_mfma_f32_16x16x32_bf16 v[100:103], v[168:171], v[180:183], v[100:103]
	ds_read_b128 v[168:171], v192 offset:2368
	v_mfma_f32_16x16x32_bf16 v[96:99], v[172:175], v[180:183], v[96:99]
	ds_read_b128 v[172:175], v192 offset:4672
	v_mfma_f32_16x16x32_bf16 v[36:39], v[164:167], v[180:183], v[36:39]
	ds_read_b128 v[164:167], v192 offset:6976
	v_mfma_f32_16x16x32_bf16 v[32:35], v[160:163], v[180:183], v[32:35]
	ds_read_b128 v[160:163], v192 offset:9280
	ds_read_b128 v[180:183], v192 offset:11584
	s_waitcnt lgkmcnt(5)
	v_mfma_f32_16x16x32_bf16 v[156:159], v[176:179], v[248:251], v[156:159]
	v_mfma_f32_16x16x32_bf16 v[152:155], v[216:219], v[248:251], v[152:155]
	v_mfma_f32_16x16x32_bf16 v[92:95], v[188:191], v[248:251], v[92:95]
	v_mfma_f32_16x16x32_bf16 v[88:91], v[184:187], v[248:251], v[88:91]
	ds_read_b128 v[248:251], v192 offset:13888
	s_waitcnt lgkmcnt(5)
	v_mfma_f32_16x16x32_bf16 v[148:151], v[176:179], v[168:171], v[148:151]
	v_mfma_f32_16x16x32_bf16 v[144:147], v[216:219], v[168:171], v[144:147]
	v_mfma_f32_16x16x32_bf16 v[84:87], v[188:191], v[168:171], v[84:87]
	v_mfma_f32_16x16x32_bf16 v[80:83], v[184:187], v[168:171], v[80:83]
	ds_read_b128 v[168:171], v192 offset:16192
	s_waitcnt lgkmcnt(5)
	v_mfma_f32_16x16x32_bf16 v[140:143], v[176:179], v[172:175], v[140:143]
	v_mfma_f32_16x16x32_bf16 v[136:139], v[216:219], v[172:175], v[136:139]
	v_mfma_f32_16x16x32_bf16 v[76:79], v[188:191], v[172:175], v[76:79]
	v_mfma_f32_16x16x32_bf16 v[72:75], v[184:187], v[172:175], v[72:75]
	s_bitcmp1_b32 s52, 0
	s_cselect_b32 s1, 0x12000, 0
	v_or_b32_e32 v172, s1, v194
	v_add_u32_e32 v172, v172, v241
	s_waitcnt vmcnt(7)
	ds_write_b128 v172, v[0:3]
	s_waitcnt vmcnt(6)
	ds_write_b128 v172, v[4:7] offset:9216
	s_waitcnt lgkmcnt(6)
	v_mfma_f32_16x16x32_bf16 v[132:135], v[176:179], v[164:167], v[132:135]
	v_mfma_f32_16x16x32_bf16 v[128:131], v[216:219], v[164:167], v[128:131]
	v_mfma_f32_16x16x32_bf16 v[68:71], v[188:191], v[164:167], v[68:71]
	v_mfma_f32_16x16x32_bf16 v[64:67], v[184:187], v[164:167], v[64:67]
	s_waitcnt vmcnt(5)
	ds_write_b128 v172, v[8:11] offset:18432
	s_waitcnt vmcnt(4)
	ds_write_b128 v172, v[12:15] offset:27648
	s_waitcnt lgkmcnt(7)
	v_mfma_f32_16x16x32_bf16 v[124:127], v[176:179], v[160:163], v[124:127]
	v_mfma_f32_16x16x32_bf16 v[120:123], v[216:219], v[160:163], v[120:123]
	v_mfma_f32_16x16x32_bf16 v[60:63], v[188:191], v[160:163], v[60:63]
	v_mfma_f32_16x16x32_bf16 v[56:59], v[184:187], v[160:163], v[56:59]
	s_waitcnt vmcnt(3)
	ds_write_b128 v172, v[16:19] offset:36864
	s_waitcnt vmcnt(2)
	ds_write_b128 v172, v[20:23] offset:46080
	s_waitcnt lgkmcnt(8)
	v_mfma_f32_16x16x32_bf16 v[116:119], v[176:179], v[180:183], v[116:119]
	v_mfma_f32_16x16x32_bf16 v[112:115], v[216:219], v[180:183], v[112:115]
	v_mfma_f32_16x16x32_bf16 v[52:55], v[188:191], v[180:183], v[52:55]
	v_mfma_f32_16x16x32_bf16 v[48:51], v[184:187], v[180:183], v[48:51]
	s_waitcnt vmcnt(1)
	ds_write_b128 v172, v[24:27] offset:55296
	s_waitcnt vmcnt(0)
	ds_write_b128 v172, v[28:31] offset:64512

; #define MFMA16(a, b, c) __builtin_amdgcn_mfma_f32_16x16x32_bf16((a), (b), (c), 0, 0, 0)
;     ...
;       for (int gi = 0; gi < NG; ++gi) {
;         const int ks = gi / HG;
;         if (gi + 1 < NG) {
;           const int ks1 = (gi + 1) / HG, h1 = (gi + 1) % HG;
;           if (ks1 != ks) {
; #pragma unroll
;             for (int j = 0; j < 4; ++j) fb[ks1 & 1][j] = *(const bf16x8*)(pB + (j * 16) * LDSS + ks1 * 32);
;           }
; #pragma unroll
;           for (int i = 0; i < FA; ++i) fa[(gi + 1) & 1][i] = *(const bf16x8*)(pA + ((h1 * FA + i) * 16) * LDSS + ks1 * 32);
;         }
;         const int h = gi % HG;
; #pragma unroll
;         for (int i = 0; i < FA; ++i)
; #pragma unroll
;           for (int j = 0; j < 4; ++j)
;             acc[h * FA + i][j] = NAT ? MFMA16(fa[gi & 1][i], fb[ks & 1][j], acc[h * FA + i][j]) : MFMA16(fb[ks & 1][j], fa[gi & 1][i], acc[h * FA + i][j]);
;         __builtin_amdgcn_sched_barrier(0);
;       }
;     }
;     if (kt == nk - 1) {
.LBB0_1286:
	s_waitcnt lgkmcnt(9)
	v_mfma_f32_16x16x32_bf16 v[108:111], v[176:179], v[248:251], v[108:111]
	v_mfma_f32_16x16x32_bf16 v[104:107], v[216:219], v[248:251], v[104:107]
	v_mfma_f32_16x16x32_bf16 v[44:47], v[188:191], v[248:251], v[44:47]
	v_mfma_f32_16x16x32_bf16 v[40:43], v[184:187], v[248:251], v[40:43]
	s_waitcnt lgkmcnt(8)
	v_mfma_f32_16x16x32_bf16 v[100:103], v[176:179], v[168:171], v[100:103]
	v_mfma_f32_16x16x32_bf16 v[96:99], v[216:219], v[168:171], v[96:99]
	v_mfma_f32_16x16x32_bf16 v[36:39], v[188:191], v[168:171], v[36:39]
	v_mfma_f32_16x16x32_bf16 v[32:35], v[184:187], v[168:171], v[32:35]
	s_waitcnt lgkmcnt(0)
	s_cmp_lg_u32 s14, 3
	s_mov_b64 s[0:1], -1
	s_cbranch_scc0 .LBB0_1288
	s_add_i32 s14, s14, 1
	s_mov_b64 s[0:1], 0

; #define MFMA16(a, b, c) __builtin_amdgcn_mfma_f32_16x16x32_bf16((a), (b), (c), 0, 0, 0)
;     ...
;     bf16_t* sA = sm + (q & 1) * STG; bf16_t* sB = sA + BM * LDSS;
;     constexpr int FA = MI < 4 ? MI : 4, HG = MI / FA, NG = 2 * HG;
;     bf16x8 fb[2][4], fa[2][FA];
;     const bf16_t* pA = sA + (wm * MI * 16) * LDSS + fro; const bf16_t* pB = sB + (wn * 64) * LDSS + fro;
; #pragma unroll
;     for (int j = 0; j < 4; ++j) fb[0][j] = *(const bf16x8*)(pB + (j * 16) * LDSS);
; #pragma unroll
;     for (int i = 0; i < FA; ++i) fa[0][i] = *(const bf16x8*)(pA + (i * 16) * LDSS);
;     __builtin_amdgcn_sched_barrier(0);
;     if (q + 1 < Q) {
;       bf16_t* nA = sm + ((q + 1) & 1) * STG; bf16_t* nB = nA + BM * LDSS;
; #pragma unroll
;       for (int i = 0; i < AR; ++i) *(u32x4*)(nA + (lr + 64 * i) * LDSS + lc) = ra[i];
; #pragma unroll
;       for (int i = 0; i < BR; ++i) *(u32x4*)(nB + (lr + 64 * i) * LDSS + lc) = rb[i];
;     }
;     if (q + 2 < Q) {
;       int kt2 = kt + 2;
;       if (kt2 >= nk) { kt2 -= nk; if (kt2 == 0) set_offs(jt + 1); }
;       const char* gk = gb + kt2 * 128;
; #pragma unroll
;       for (int i = 0; i < AR; ++i) ra[i] = *(const u32x4*)(gk + ap[i]);
; #pragma unroll
;       for (int i = 0; i < BR; ++i) rb[i] = *(const u32x4*)(gk + bp[i]);
;     }
;     __builtin_amdgcn_sched_barrier(0);
;     {
; #pragma unroll
;       for (int gi = 0; gi < NG; ++gi) {
;         const int ks = gi / HG;
;         if (gi + 1 < NG) {
;           const int ks1 = (gi + 1) / HG, h1 = (gi + 1) % HG;
;           if (ks1 != ks) {
; #pragma unroll
;             for (int j = 0; j < 4; ++j) fb[ks1 & 1][j] = *(const bf16x8*)(pB + (j * 16) * LDSS + ks1 * 32);
;           }
; #pragma unroll
;           for (int i = 0; i < FA; ++i) fa[(gi + 1) & 1][i] = *(const bf16x8*)(pA + ((h1 * FA + i) * 16) * LDSS + ks1 * 32);
;         }
;         const int h = gi % HG;
; #pragma unroll
;         for (int i = 0; i < FA; ++i)
; #pragma unroll
;           for (int j = 0; j < 4; ++j)
;             acc[h * FA + i][j] = NAT ? MFMA16(fa[gi & 1][i], fb[ks & 1][j], acc[h * FA + i][j]) : MFMA16(fb[ks & 1][j], fa[gi & 1][i], acc[h * FA + i][j]);
;         __builtin_amdgcn_sched_barrier(0);
.LBB0_1670:
	s_bitcmp1_b32 s0, 0
	s_cselect_b32 s1, 0x12000, 0
	v_add3_u32 v242, s1, v237, v241
	v_add3_u32 v192, s1, v236, v241
	ds_read_b128 v[168:171], v242 offset:36864
	ds_read_b128 v[188:191], v192
	ds_read_b128 v[172:175], v242 offset:39168
	ds_read_b128 v[164:167], v242 offset:41472
	ds_read_b128 v[160:163], v242 offset:43776
	ds_read_b128 v[184:187], v192 offset:2304
	ds_read_b128 v[180:183], v192 offset:4608
	ds_read_b128 v[176:179], v192 offset:6912
	s_add_i32 s31, s0, 1
	s_waitcnt lgkmcnt(6)
	v_mfma_f32_16x16x32_bf16 v[156:159], v[168:171], v[188:191], v[156:159]
	s_waitcnt lgkmcnt(5)
	v_mfma_f32_16x16x32_bf16 v[152:155], v[172:175], v[188:191], v[152:155]
	s_waitcnt lgkmcnt(4)
	v_mfma_f32_16x16x32_bf16 v[148:151], v[164:167], v[188:191], v[148:151]
	s_waitcnt lgkmcnt(3)
	v_mfma_f32_16x16x32_bf16 v[144:147], v[160:163], v[188:191], v[144:147]
	ds_read_b128 v[216:219], v192 offset:9216
	ds_read_b128 v[188:191], v192 offset:11520
	s_waitcnt lgkmcnt(4)
	v_mfma_f32_16x16x32_bf16 v[140:143], v[168:171], v[184:187], v[140:143]
	v_mfma_f32_16x16x32_bf16 v[136:139], v[172:175], v[184:187], v[136:139]
	v_mfma_f32_16x16x32_bf16 v[132:135], v[164:167], v[184:187], v[132:135]
	v_mfma_f32_16x16x32_bf16 v[128:131], v[160:163], v[184:187], v[128:131]
	ds_read_b128 v[184:187], v192 offset:13824
	s_waitcnt lgkmcnt(4)
	v_mfma_f32_16x16x32_bf16 v[124:127], v[168:171], v[180:183], v[124:127]
	v_mfma_f32_16x16x32_bf16 v[120:123], v[172:175], v[180:183], v[120:123]
	v_mfma_f32_16x16x32_bf16 v[116:119], v[164:167], v[180:183], v[116:119]
	v_mfma_f32_16x16x32_bf16 v[112:115], v[160:163], v[180:183], v[112:115]
	ds_read_b128 v[180:183], v192 offset:16128
	s_waitcnt lgkmcnt(4)
	v_mfma_f32_16x16x32_bf16 v[108:111], v[168:171], v[176:179], v[108:111]
	v_mfma_f32_16x16x32_bf16 v[104:107], v[172:175], v[176:179], v[104:107]
	v_mfma_f32_16x16x32_bf16 v[100:103], v[164:167], v[176:179], v[100:103]
	v_mfma_f32_16x16x32_bf16 v[96:99], v[160:163], v[176:179], v[96:99]
	ds_read_b128 v[176:179], v242 offset:36928
	s_waitcnt lgkmcnt(4)
	v_mfma_f32_16x16x32_bf16 v[92:95], v[168:171], v[216:219], v[92:95]
	v_mfma_f32_16x16x32_bf16 v[88:91], v[172:175], v[216:219], v[88:91]
	v_mfma_f32_16x16x32_bf16 v[84:87], v[164:167], v[216:219], v[84:87]
	v_mfma_f32_16x16x32_bf16 v[80:83], v[160:163], v[216:219], v[80:83]
	ds_read_b128 v[216:219], v242 offset:39232
	s_waitcnt lgkmcnt(4)
	v_mfma_f32_16x16x32_bf16 v[76:79], v[168:171], v[188:191], v[76:79]
	v_mfma_f32_16x16x32_bf16 v[72:75], v[172:175], v[188:191], v[72:75]
	v_mfma_f32_16x16x32_bf16 v[68:71], v[164:167], v[188:191], v[68:71]
	v_mfma_f32_16x16x32_bf16 v[64:67], v[160:163], v[188:191], v[64:67]
	ds_read_b128 v[188:191], v242 offset:41536
	s_waitcnt lgkmcnt(4)
	v_mfma_f32_16x16x32_bf16 v[60:63], v[168:171], v[184:187], v[60:63]
	v_mfma_f32_16x16x32_bf16 v[56:59], v[172:175], v[184:187], v[56:59]
	v_mfma_f32_16x16x32_bf16 v[52:55], v[164:167], v[184:187], v[52:55]
	v_mfma_f32_16x16x32_bf16 v[48:51], v[160:163], v[184:187], v[48:51]
	ds_read_b128 v[184:187], v242 offset:43840
	ds_read_b128 v[242:245], v192 offset:64
	s_waitcnt lgkmcnt(5)
	v_mfma_f32_16x16x32_bf16 v[44:47], v[168:171], v[180:183], v[44:47]
	ds_read_b128 v[168:171], v192 offset:2368
	v_mfma_f32_16x16x32_bf16 v[40:43], v[172:175], v[180:183], v[40:43]
	ds_read_b128 v[172:175], v192 offset:4672
	v_mfma_f32_16x16x32_bf16 v[36:39], v[164:167], v[180:183], v[36:39]
	ds_read_b128 v[164:167], v192 offset:6976
	v_mfma_f32_16x16x32_bf16 v[0:3], v[160:163], v[180:183], v[0:3]
	ds_read_b128 v[160:163], v192 offset:9280
	ds_read_b128 v[180:183], v192 offset:11584
	s_waitcnt lgkmcnt(5)
	v_mfma_f32_16x16x32_bf16 v[156:159], v[176:179], v[242:245], v[156:159]
	v_mfma_f32_16x16x32_bf16 v[152:155], v[216:219], v[242:245], v[152:155]
	v_mfma_f32_16x16x32_bf16 v[148:151], v[188:191], v[242:245], v[148:151]
	v_mfma_f32_16x16x32_bf16 v[144:147], v[184:187], v[242:245], v[144:147]
	ds_read_b128 v[242:245], v192 offset:13888
	s_waitcnt lgkmcnt(5)
	v_mfma_f32_16x16x32_bf16 v[140:143], v[176:179], v[168:171], v[140:143]
	v_mfma_f32_16x16x32_bf16 v[136:139], v[216:219], v[168:171], v[136:139]
	v_mfma_f32_16x16x32_bf16 v[132:135], v[188:191], v[168:171], v[132:135]
	v_mfma_f32_16x16x32_bf16 v[128:131], v[184:187], v[168:171], v[128:131]
	ds_read_b128 v[168:171], v192 offset:16192
	s_waitcnt lgkmcnt(5)
	v_mfma_f32_16x16x32_bf16 v[124:127], v[176:179], v[172:175], v[124:127]
	v_mfma_f32_16x16x32_bf16 v[120:123], v[216:219], v[172:175], v[120:123]
	v_mfma_f32_16x16x32_bf16 v[116:119], v[188:191], v[172:175], v[116:119]
	v_mfma_f32_16x16x32_bf16 v[112:115], v[184:187], v[172:175], v[112:115]
	s_bitcmp1_b32 s31, 0
	s_cselect_b32 s1, 0x12000, 0
	v_or_b32_e32 v172, s1, v195
	v_add_u32_e32 v172, v172, v199
	s_waitcnt vmcnt(7)
	ds_write_b128 v172, v[4:7]
	s_waitcnt vmcnt(6)
	ds_write_b128 v172, v[8:11] offset:9216
	s_waitcnt lgkmcnt(6)
	v_mfma_f32_16x16x32_bf16 v[108:111], v[176:179], v[164:167], v[108:111]
	v_mfma_f32_16x16x32_bf16 v[104:107], v[216:219], v[164:167], v[104:107]
	v_mfma_f32_16x16x32_bf16 v[100:103], v[188:191], v[164:167], v[100:103]
	v_mfma_f32_16x16x32_bf16 v[96:99], v[184:187], v[164:167], v[96:99]
	s_waitcnt vmcnt(5)
	ds_write_b128 v172, v[12:15] offset:18432
	s_waitcnt vmcnt(4)
	ds_write_b128 v172, v[16:19] offset:27648
	s_waitcnt lgkmcnt(7)
	v_mfma_f32_16x16x32_bf16 v[92:95], v[176:179], v[160:163], v[92:95]
	v_mfma_f32_16x16x32_bf16 v[88:91], v[216:219], v[160:163], v[88:91]
	v_mfma_f32_16x16x32_bf16 v[84:87], v[188:191], v[160:163], v[84:87]
	v_mfma_f32_16x16x32_bf16 v[80:83], v[184:187], v[160:163], v[80:83]
	s_waitcnt vmcnt(3)
	ds_write_b128 v172, v[20:23] offset:36864
	s_waitcnt vmcnt(2)
	ds_write_b128 v172, v[24:27] offset:46080
	s_waitcnt lgkmcnt(8)
	v_mfma_f32_16x16x32_bf16 v[76:79], v[176:179], v[180:183], v[76:79]
	v_mfma_f32_16x16x32_bf16 v[72:75], v[216:219], v[180:183], v[72:75]
	v_mfma_f32_16x16x32_bf16 v[68:71], v[188:191], v[180:183], v[68:71]
	v_mfma_f32_16x16x32_bf16 v[64:67], v[184:187], v[180:183], v[64:67]
	s_waitcnt vmcnt(1)
	ds_write_b128 v172, v[28:31] offset:55296
	s_waitcnt vmcnt(0)
	ds_write_b128 v172, v[32:35] offset:64512

; #define MFMA16(a, b, c) __builtin_amdgcn_mfma_f32_16x16x32_bf16((a), (b), (c), 0, 0, 0)
;     ...
;         const int h = gi % HG;
; #pragma unroll
;         for (int i = 0; i < FA; ++i)
; #pragma unroll
;           for (int j = 0; j < 4; ++j)
;             acc[h * FA + i][j] = NAT ? MFMA16(fa[gi & 1][i], fb[ks & 1][j], acc[h * FA + i][j]) : MFMA16(fb[ks & 1][j], fa[gi & 1][i], acc[h * FA + i][j]);
;         __builtin_amdgcn_sched_barrier(0);
;       }
;     }
;     if (kt == nk - 1) {
;       int mt, nt; tile_at(jt, mt, nt);
;       f(mt, nt, [&](auto&& a, auto&& bfn, auto&& ep) { ep(acc, wm, wn, lane); });
; #pragma unroll
;       for (int i = 0; i < MI; ++i)
; #pragma unroll
;         for (int j = 0; j < 4; ++j) acc[i][j] = (f32x4){0.f, 0.f, 0.f, 0.f};
;       kt = 0; ++jt;
;     } else ++kt;
.LBB0_1682:
	s_waitcnt lgkmcnt(9)
	v_mfma_f32_16x16x32_bf16 v[60:63], v[176:179], v[242:245], v[60:63]
	v_mfma_f32_16x16x32_bf16 v[56:59], v[216:219], v[242:245], v[56:59]
	v_mfma_f32_16x16x32_bf16 v[52:55], v[188:191], v[242:245], v[52:55]
	v_mfma_f32_16x16x32_bf16 v[48:51], v[184:187], v[242:245], v[48:51]
	s_waitcnt lgkmcnt(8)
	v_mfma_f32_16x16x32_bf16 v[44:47], v[176:179], v[168:171], v[44:47]
	v_mfma_f32_16x16x32_bf16 v[40:43], v[216:219], v[168:171], v[40:43]
	v_mfma_f32_16x16x32_bf16 v[36:39], v[188:191], v[168:171], v[36:39]
	v_mfma_f32_16x16x32_bf16 v[0:3], v[184:187], v[168:171], v[0:3]
	s_waitcnt lgkmcnt(0)
	s_cmp_lg_u32 s40, 15
	s_mov_b64 s[0:1], -1
	s_cbranch_scc0 .LBB0_1684
	s_add_i32 s40, s40, 1
	s_mov_b64 s[0:1], 0

; #define MFMA16(a, b, c) __builtin_amdgcn_mfma_f32_16x16x32_bf16((a), (b), (c), 0, 0, 0)
;     ...
;     bf16_t* sA = sm + (q & 1) * STG; bf16_t* sB = sA + BM * LDSS;
;     constexpr int FA = MI < 4 ? MI : 4, HG = MI / FA, NG = 2 * HG;
;     bf16x8 fb[2][4], fa[2][FA];
;     const bf16_t* pA = sA + (wm * MI * 16) * LDSS + fro; const bf16_t* pB = sB + (wn * 64) * LDSS + fro;
; #pragma unroll
;     for (int j = 0; j < 4; ++j) fb[0][j] = *(const bf16x8*)(pB + (j * 16) * LDSS);
; #pragma unroll
;     for (int i = 0; i < FA; ++i) fa[0][i] = *(const bf16x8*)(pA + (i * 16) * LDSS);
;     __builtin_amdgcn_sched_barrier(0);
;     if (q + 1 < Q) {
;       bf16_t* nA = sm + ((q + 1) & 1) * STG; bf16_t* nB = nA + BM * LDSS;
; #pragma unroll
;       for (int i = 0; i < AR; ++i) *(u32x4*)(nA + (lr + 64 * i) * LDSS + lc) = ra[i];
; #pragma unroll
;       for (int i = 0; i < BR; ++i) *(u32x4*)(nB + (lr + 64 * i) * LDSS + lc) = rb[i];
;     }
;     if (q + 2 < Q) {
;       int kt2 = kt + 2;
;       if (kt2 >= nk) { kt2 -= nk; if (kt2 == 0) set_offs(jt + 1); }
;       const char* gk = gb + kt2 * 128;
; #pragma unroll
;       for (int i = 0; i < AR; ++i) ra[i] = *(const u32x4*)(gk + ap[i]);
; #pragma unroll
;       for (int i = 0; i < BR; ++i) rb[i] = *(const u32x4*)(gk + bp[i]);
;     }
;     __builtin_amdgcn_sched_barrier(0);
;     {
; #pragma unroll
;       for (int gi = 0; gi < NG; ++gi) {
;         const int ks = gi / HG;
;         if (gi + 1 < NG) {
;           const int ks1 = (gi + 1) / HG, h1 = (gi + 1) % HG;
;           if (ks1 != ks) {
; #pragma unroll
;             for (int j = 0; j < 4; ++j) fb[ks1 & 1][j] = *(const bf16x8*)(pB + (j * 16) * LDSS + ks1 * 32);
;           }
; #pragma unroll
;           for (int i = 0; i < FA; ++i) fa[(gi + 1) & 1][i] = *(const bf16x8*)(pA + ((h1 * FA + i) * 16) * LDSS + ks1 * 32);
;         }
;         const int h = gi % HG;
; #pragma unroll
;         for (int i = 0; i < FA; ++i)
; #pragma unroll
;           for (int j = 0; j < 4; ++j)
;             acc[h * FA + i][j] = NAT ? MFMA16(fa[gi & 1][i], fb[ks & 1][j], acc[h * FA + i][j]) : MFMA16(fb[ks & 1][j], fa[gi & 1][i], acc[h * FA + i][j]);
;         __builtin_amdgcn_sched_barrier(0);
.LBB0_2049:
	s_bitcmp1_b32 s0, 0
	s_cselect_b32 s1, 0x12000, 0
	v_add3_u32 v244, s1, v233, v202
	v_add3_u32 v243, s1, v231, v202
	ds_read_b128 v[168:171], v244 offset:36864
	ds_read_b128 v[188:191], v243
	ds_read_b128 v[172:175], v244 offset:39168
	ds_read_b128 v[164:167], v244 offset:41472
	ds_read_b128 v[160:163], v244 offset:43776
	ds_read_b128 v[184:187], v243 offset:2304
	ds_read_b128 v[180:183], v243 offset:4608
	ds_read_b128 v[176:179], v243 offset:6912
	s_add_i32 s3, s0, 1
	s_waitcnt lgkmcnt(6)
	v_mfma_f32_16x16x32_bf16 v[156:159], v[168:171], v[188:191], v[156:159]
	s_waitcnt lgkmcnt(5)
	v_mfma_f32_16x16x32_bf16 v[148:151], v[172:175], v[188:191], v[148:151]
	s_waitcnt lgkmcnt(4)
	v_mfma_f32_16x16x32_bf16 v[152:155], v[164:167], v[188:191], v[152:155]
	s_waitcnt lgkmcnt(3)
	v_mfma_f32_16x16x32_bf16 v[144:147], v[160:163], v[188:191], v[144:147]
	ds_read_b128 v[216:219], v243 offset:9216
	ds_read_b128 v[188:191], v243 offset:11520
	s_waitcnt lgkmcnt(4)
	v_mfma_f32_16x16x32_bf16 v[140:143], v[168:171], v[184:187], v[140:143]
	v_mfma_f32_16x16x32_bf16 v[132:135], v[172:175], v[184:187], v[132:135]
	v_mfma_f32_16x16x32_bf16 v[136:139], v[164:167], v[184:187], v[136:139]
	v_mfma_f32_16x16x32_bf16 v[128:131], v[160:163], v[184:187], v[128:131]
	ds_read_b128 v[184:187], v243 offset:13824
	s_waitcnt lgkmcnt(4)
	v_mfma_f32_16x16x32_bf16 v[124:127], v[168:171], v[180:183], v[124:127]
	v_mfma_f32_16x16x32_bf16 v[116:119], v[172:175], v[180:183], v[116:119]
	v_mfma_f32_16x16x32_bf16 v[120:123], v[164:167], v[180:183], v[120:123]
	v_mfma_f32_16x16x32_bf16 v[112:115], v[160:163], v[180:183], v[112:115]
	ds_read_b128 v[180:183], v243 offset:16128
	s_waitcnt lgkmcnt(4)
	v_mfma_f32_16x16x32_bf16 v[108:111], v[168:171], v[176:179], v[108:111]
	v_mfma_f32_16x16x32_bf16 v[100:103], v[172:175], v[176:179], v[100:103]
	v_mfma_f32_16x16x32_bf16 v[104:107], v[164:167], v[176:179], v[104:107]
	v_mfma_f32_16x16x32_bf16 v[96:99], v[160:163], v[176:179], v[96:99]
	ds_read_b128 v[176:179], v244 offset:36928
	s_waitcnt lgkmcnt(4)
	v_mfma_f32_16x16x32_bf16 v[92:95], v[168:171], v[216:219], v[92:95]
	v_mfma_f32_16x16x32_bf16 v[84:87], v[172:175], v[216:219], v[84:87]
	v_mfma_f32_16x16x32_bf16 v[88:91], v[164:167], v[216:219], v[88:91]
	v_mfma_f32_16x16x32_bf16 v[80:83], v[160:163], v[216:219], v[80:83]
	ds_read_b128 v[216:219], v244 offset:39232
	s_waitcnt lgkmcnt(4)
	v_mfma_f32_16x16x32_bf16 v[76:79], v[168:171], v[188:191], v[76:79]
	v_mfma_f32_16x16x32_bf16 v[72:75], v[172:175], v[188:191], v[72:75]
	v_mfma_f32_16x16x32_bf16 v[68:71], v[164:167], v[188:191], v[68:71]
	v_mfma_f32_16x16x32_bf16 v[64:67], v[160:163], v[188:191], v[64:67]
	ds_read_b128 v[188:191], v244 offset:41536
	s_waitcnt lgkmcnt(4)
	v_mfma_f32_16x16x32_bf16 v[28:31], v[168:171], v[184:187], v[28:31]
	v_mfma_f32_16x16x32_bf16 v[20:23], v[172:175], v[184:187], v[20:23]
	v_mfma_f32_16x16x32_bf16 v[24:27], v[164:167], v[184:187], v[24:27]
	v_mfma_f32_16x16x32_bf16 v[16:19], v[160:163], v[184:187], v[16:19]
	ds_read_b128 v[184:187], v244 offset:43840
	ds_read_b128 v[244:247], v243 offset:64
	s_waitcnt lgkmcnt(5)
	v_mfma_f32_16x16x32_bf16 v[12:15], v[168:171], v[180:183], v[12:15]
	ds_read_b128 v[168:171], v243 offset:2368
	v_mfma_f32_16x16x32_bf16 v[8:11], v[172:175], v[180:183], v[8:11]
	ds_read_b128 v[172:175], v243 offset:4672
	v_mfma_f32_16x16x32_bf16 v[4:7], v[164:167], v[180:183], v[4:7]
	ds_read_b128 v[164:167], v243 offset:6976
	v_mfma_f32_16x16x32_bf16 v[0:3], v[160:163], v[180:183], v[0:3]
	ds_read_b128 v[160:163], v243 offset:9280
	ds_read_b128 v[180:183], v243 offset:11584
	s_waitcnt lgkmcnt(5)
	v_mfma_f32_16x16x32_bf16 v[156:159], v[176:179], v[244:247], v[156:159]
	v_mfma_f32_16x16x32_bf16 v[148:151], v[216:219], v[244:247], v[148:151]
	v_mfma_f32_16x16x32_bf16 v[152:155], v[188:191], v[244:247], v[152:155]
	v_mfma_f32_16x16x32_bf16 v[144:147], v[184:187], v[244:247], v[144:147]
	ds_read_b128 v[244:247], v243 offset:13888
	s_waitcnt lgkmcnt(5)
	v_mfma_f32_16x16x32_bf16 v[140:143], v[176:179], v[168:171], v[140:143]
	v_mfma_f32_16x16x32_bf16 v[132:135], v[216:219], v[168:171], v[132:135]
	v_mfma_f32_16x16x32_bf16 v[136:139], v[188:191], v[168:171], v[136:139]
	v_mfma_f32_16x16x32_bf16 v[128:131], v[184:187], v[168:171], v[128:131]
	ds_read_b128 v[168:171], v243 offset:16192
	s_waitcnt lgkmcnt(5)
	v_mfma_f32_16x16x32_bf16 v[124:127], v[176:179], v[172:175], v[124:127]
	v_mfma_f32_16x16x32_bf16 v[116:119], v[216:219], v[172:175], v[116:119]
	v_mfma_f32_16x16x32_bf16 v[120:123], v[188:191], v[172:175], v[120:123]
	v_mfma_f32_16x16x32_bf16 v[112:115], v[184:187], v[172:175], v[112:115]
	s_bitcmp1_b32 s3, 0
	s_cselect_b32 s1, 0x12000, 0
	v_or_b32_e32 v172, s1, v196
	v_add_u32_e32 v172, v172, v200
	s_waitcnt vmcnt(3)
	ds_write_b128 v172, v[36:39]
	s_waitcnt vmcnt(2)
	ds_write_b128 v172, v[44:47] offset:9216
	s_waitcnt lgkmcnt(6)
	v_mfma_f32_16x16x32_bf16 v[108:111], v[176:179], v[164:167], v[108:111]
	v_mfma_f32_16x16x32_bf16 v[100:103], v[216:219], v[164:167], v[100:103]
	v_mfma_f32_16x16x32_bf16 v[104:107], v[188:191], v[164:167], v[104:107]
	v_mfma_f32_16x16x32_bf16 v[96:99], v[184:187], v[164:167], v[96:99]
	s_waitcnt vmcnt(1)
	ds_write_b128 v172, v[52:55] offset:18432
	s_waitcnt vmcnt(0)
	ds_write_b128 v172, v[60:63] offset:27648
	s_waitcnt lgkmcnt(7)
	v_mfma_f32_16x16x32_bf16 v[92:95], v[176:179], v[160:163], v[92:95]
	v_mfma_f32_16x16x32_bf16 v[84:87], v[216:219], v[160:163], v[84:87]
	v_mfma_f32_16x16x32_bf16 v[88:91], v[188:191], v[160:163], v[88:91]
	v_mfma_f32_16x16x32_bf16 v[80:83], v[184:187], v[160:163], v[80:83]
	ds_write_b128 v172, v[32:35] offset:36864
	ds_write_b128 v172, v[40:43] offset:46080
	s_waitcnt lgkmcnt(8)
	v_mfma_f32_16x16x32_bf16 v[76:79], v[176:179], v[180:183], v[76:79]
	v_mfma_f32_16x16x32_bf16 v[72:75], v[216:219], v[180:183], v[72:75]
	v_mfma_f32_16x16x32_bf16 v[68:71], v[188:191], v[180:183], v[68:71]
	v_mfma_f32_16x16x32_bf16 v[64:67], v[184:187], v[180:183], v[64:67]
	ds_write_b128 v172, v[48:51] offset:55296
	ds_write_b128 v172, v[56:59] offset:64512

; #define MFMA16(a, b, c) __builtin_amdgcn_mfma_f32_16x16x32_bf16((a), (b), (c), 0, 0, 0)
;     ...
;         const int h = gi % HG;
; #pragma unroll
;         for (int i = 0; i < FA; ++i)
; #pragma unroll
;           for (int j = 0; j < 4; ++j)
;             acc[h * FA + i][j] = NAT ? MFMA16(fa[gi & 1][i], fb[ks & 1][j], acc[h * FA + i][j]) : MFMA16(fb[ks & 1][j], fa[gi & 1][i], acc[h * FA + i][j]);
;         __builtin_amdgcn_sched_barrier(0);
;       }
;     }
;     if (kt == nk - 1) {
;       int mt, nt; tile_at(jt, mt, nt);
;       f(mt, nt, [&](auto&& a, auto&& bfn, auto&& ep) { ep(acc, wm, wn, lane); });
; #pragma unroll
;       for (int i = 0; i < MI; ++i)
; #pragma unroll
;         for (int j = 0; j < 4; ++j) acc[i][j] = (f32x4){0.f, 0.f, 0.f, 0.f};
;       kt = 0; ++jt;
;     } else ++kt;
.LBB0_2061:
	s_waitcnt lgkmcnt(9)
	v_mfma_f32_16x16x32_bf16 v[28:31], v[176:179], v[244:247], v[28:31]
	v_mfma_f32_16x16x32_bf16 v[20:23], v[216:219], v[244:247], v[20:23]
	v_mfma_f32_16x16x32_bf16 v[24:27], v[188:191], v[244:247], v[24:27]
	v_mfma_f32_16x16x32_bf16 v[16:19], v[184:187], v[244:247], v[16:19]
	s_waitcnt lgkmcnt(8)
	v_mfma_f32_16x16x32_bf16 v[12:15], v[176:179], v[168:171], v[12:15]
	v_mfma_f32_16x16x32_bf16 v[8:11], v[216:219], v[168:171], v[8:11]
	v_mfma_f32_16x16x32_bf16 v[4:7], v[188:191], v[168:171], v[4:7]
	v_mfma_f32_16x16x32_bf16 v[0:3], v[184:187], v[168:171], v[0:3]
	s_waitcnt lgkmcnt(0)
	s_cmp_lg_u32 s18, 15
	s_mov_b64 s[0:1], -1
	s_cbranch_scc0 .LBB0_2063
	s_add_i32 s18, s18, 1
	s_mov_b64 s[0:1], 0

; #define MFMA16(a, b, c) __builtin_amdgcn_mfma_f32_16x16x32_bf16((a), (b), (c), 0, 0, 0)
;     ...
;     bf16_t* sA = sm + (q & 1) * STG; bf16_t* sB = sA + BM * LDSS;
;     constexpr int FA = MI < 4 ? MI : 4, HG = MI / FA, NG = 2 * HG;
;     bf16x8 fb[2][4], fa[2][FA];
;     const bf16_t* pA = sA + (wm * MI * 16) * LDSS + fro; const bf16_t* pB = sB + (wn * 64) * LDSS + fro;
; #pragma unroll
;     for (int j = 0; j < 4; ++j) fb[0][j] = *(const bf16x8*)(pB + (j * 16) * LDSS);
; #pragma unroll
;     for (int i = 0; i < FA; ++i) fa[0][i] = *(const bf16x8*)(pA + (i * 16) * LDSS);
;     __builtin_amdgcn_sched_barrier(0);
;     if (q + 1 < Q) {
;       bf16_t* nA = sm + ((q + 1) & 1) * STG; bf16_t* nB = nA + BM * LDSS;
; #pragma unroll
;       for (int i = 0; i < AR; ++i) *(u32x4*)(nA + (lr + 64 * i) * LDSS + lc) = ra[i];
; #pragma unroll
;       for (int i = 0; i < BR; ++i) *(u32x4*)(nB + (lr + 64 * i) * LDSS + lc) = rb[i];
;     }
;     if (q + 2 < Q) {
;       int kt2 = kt + 2;
;       if (kt2 >= nk) { kt2 -= nk; if (kt2 == 0) set_offs(jt + 1); }
;       const char* gk = gb + kt2 * 128;
; #pragma unroll
;       for (int i = 0; i < AR; ++i) ra[i] = *(const u32x4*)(gk + ap[i]);
; #pragma unroll
;       for (int i = 0; i < BR; ++i) rb[i] = *(const u32x4*)(gk + bp[i]);
;     }
;     __builtin_amdgcn_sched_barrier(0);
;     {
; #pragma unroll
;       for (int gi = 0; gi < NG; ++gi) {
;         const int ks = gi / HG;
;         if (gi + 1 < NG) {
;           const int ks1 = (gi + 1) / HG, h1 = (gi + 1) % HG;
;           if (ks1 != ks) {
; #pragma unroll
;             for (int j = 0; j < 4; ++j) fb[ks1 & 1][j] = *(const bf16x8*)(pB + (j * 16) * LDSS + ks1 * 32);
;           }
; #pragma unroll
;           for (int i = 0; i < FA; ++i) fa[(gi + 1) & 1][i] = *(const bf16x8*)(pA + ((h1 * FA + i) * 16) * LDSS + ks1 * 32);
;         }
;         const int h = gi % HG;
; #pragma unroll
;         for (int i = 0; i < FA; ++i)
; #pragma unroll
;           for (int j = 0; j < 4; ++j)
;             acc[h * FA + i][j] = NAT ? MFMA16(fa[gi & 1][i], fb[ks & 1][j], acc[h * FA + i][j]) : MFMA16(fb[ks & 1][j], fa[gi & 1][i], acc[h * FA + i][j]);
;         __builtin_amdgcn_sched_barrier(0);
.LBB0_2110:
	s_bitcmp1_b32 s0, 0
	s_cselect_b32 s1, 0x12000, 0
	v_add3_u32 v244, s1, v233, v202
	v_add3_u32 v243, s1, v231, v202
	ds_read_b128 v[168:171], v244 offset:36864
	ds_read_b128 v[188:191], v243
	ds_read_b128 v[172:175], v244 offset:39168
	ds_read_b128 v[164:167], v244 offset:41472
	ds_read_b128 v[160:163], v244 offset:43776
	ds_read_b128 v[184:187], v243 offset:2304
	ds_read_b128 v[180:183], v243 offset:4608
	ds_read_b128 v[176:179], v243 offset:6912
	s_add_i32 s57, s0, 1
	s_waitcnt lgkmcnt(6)
	v_mfma_f32_16x16x32_bf16 v[156:159], v[168:171], v[188:191], v[156:159]
	s_waitcnt lgkmcnt(5)
	v_mfma_f32_16x16x32_bf16 v[148:151], v[172:175], v[188:191], v[148:151]
	s_waitcnt lgkmcnt(4)
	v_mfma_f32_16x16x32_bf16 v[152:155], v[164:167], v[188:191], v[152:155]
	s_waitcnt lgkmcnt(3)
	v_mfma_f32_16x16x32_bf16 v[144:147], v[160:163], v[188:191], v[144:147]
	ds_read_b128 v[216:219], v243 offset:9216
	ds_read_b128 v[188:191], v243 offset:11520
	s_waitcnt lgkmcnt(4)
	v_mfma_f32_16x16x32_bf16 v[140:143], v[168:171], v[184:187], v[140:143]
	v_mfma_f32_16x16x32_bf16 v[132:135], v[172:175], v[184:187], v[132:135]
	v_mfma_f32_16x16x32_bf16 v[136:139], v[164:167], v[184:187], v[136:139]
	v_mfma_f32_16x16x32_bf16 v[128:131], v[160:163], v[184:187], v[128:131]
	ds_read_b128 v[184:187], v243 offset:13824
	s_waitcnt lgkmcnt(4)
	v_mfma_f32_16x16x32_bf16 v[124:127], v[168:171], v[180:183], v[124:127]
	v_mfma_f32_16x16x32_bf16 v[116:119], v[172:175], v[180:183], v[116:119]
	v_mfma_f32_16x16x32_bf16 v[120:123], v[164:167], v[180:183], v[120:123]
	v_mfma_f32_16x16x32_bf16 v[112:115], v[160:163], v[180:183], v[112:115]
	ds_read_b128 v[180:183], v243 offset:16128
	s_waitcnt lgkmcnt(4)
	v_mfma_f32_16x16x32_bf16 v[108:111], v[168:171], v[176:179], v[108:111]
	v_mfma_f32_16x16x32_bf16 v[100:103], v[172:175], v[176:179], v[100:103]
	v_mfma_f32_16x16x32_bf16 v[104:107], v[164:167], v[176:179], v[104:107]
	v_mfma_f32_16x16x32_bf16 v[96:99], v[160:163], v[176:179], v[96:99]
	ds_read_b128 v[176:179], v244 offset:36928
	s_waitcnt lgkmcnt(4)
	v_mfma_f32_16x16x32_bf16 v[92:95], v[168:171], v[216:219], v[92:95]
	v_mfma_f32_16x16x32_bf16 v[84:87], v[172:175], v[216:219], v[84:87]
	v_mfma_f32_16x16x32_bf16 v[88:91], v[164:167], v[216:219], v[88:91]
	v_mfma_f32_16x16x32_bf16 v[80:83], v[160:163], v[216:219], v[80:83]
	ds_read_b128 v[216:219], v244 offset:39232
	s_waitcnt lgkmcnt(4)
	v_mfma_f32_16x16x32_bf16 v[76:79], v[168:171], v[188:191], v[76:79]
	v_mfma_f32_16x16x32_bf16 v[72:75], v[172:175], v[188:191], v[72:75]
	v_mfma_f32_16x16x32_bf16 v[68:71], v[164:167], v[188:191], v[68:71]
	v_mfma_f32_16x16x32_bf16 v[64:67], v[160:163], v[188:191], v[64:67]
	ds_read_b128 v[188:191], v244 offset:41536
	s_waitcnt lgkmcnt(4)
	v_mfma_f32_16x16x32_bf16 v[28:31], v[168:171], v[184:187], v[28:31]
	v_mfma_f32_16x16x32_bf16 v[20:23], v[172:175], v[184:187], v[20:23]
	v_mfma_f32_16x16x32_bf16 v[24:27], v[164:167], v[184:187], v[24:27]
	v_mfma_f32_16x16x32_bf16 v[16:19], v[160:163], v[184:187], v[16:19]
	ds_read_b128 v[184:187], v244 offset:43840
	ds_read_b128 v[244:247], v243 offset:64
	s_waitcnt lgkmcnt(5)
	v_mfma_f32_16x16x32_bf16 v[12:15], v[168:171], v[180:183], v[12:15]
	ds_read_b128 v[168:171], v243 offset:2368
	v_mfma_f32_16x16x32_bf16 v[8:11], v[172:175], v[180:183], v[8:11]
	ds_read_b128 v[172:175], v243 offset:4672
	v_mfma_f32_16x16x32_bf16 v[4:7], v[164:167], v[180:183], v[4:7]
	ds_read_b128 v[164:167], v243 offset:6976
	v_mfma_f32_16x16x32_bf16 v[0:3], v[160:163], v[180:183], v[0:3]
	ds_read_b128 v[160:163], v243 offset:9280
	ds_read_b128 v[180:183], v243 offset:11584
	s_waitcnt lgkmcnt(5)
	v_mfma_f32_16x16x32_bf16 v[156:159], v[176:179], v[244:247], v[156:159]
	v_mfma_f32_16x16x32_bf16 v[148:151], v[216:219], v[244:247], v[148:151]
	v_mfma_f32_16x16x32_bf16 v[152:155], v[188:191], v[244:247], v[152:155]
	v_mfma_f32_16x16x32_bf16 v[144:147], v[184:187], v[244:247], v[144:147]
	ds_read_b128 v[244:247], v243 offset:13888
	s_waitcnt lgkmcnt(5)
	v_mfma_f32_16x16x32_bf16 v[140:143], v[176:179], v[168:171], v[140:143]
	v_mfma_f32_16x16x32_bf16 v[132:135], v[216:219], v[168:171], v[132:135]
	v_mfma_f32_16x16x32_bf16 v[136:139], v[188:191], v[168:171], v[136:139]
	v_mfma_f32_16x16x32_bf16 v[128:131], v[184:187], v[168:171], v[128:131]
	ds_read_b128 v[168:171], v243 offset:16192
	s_waitcnt lgkmcnt(5)
	v_mfma_f32_16x16x32_bf16 v[124:127], v[176:179], v[172:175], v[124:127]
	v_mfma_f32_16x16x32_bf16 v[116:119], v[216:219], v[172:175], v[116:119]
	v_mfma_f32_16x16x32_bf16 v[120:123], v[188:191], v[172:175], v[120:123]
	v_mfma_f32_16x16x32_bf16 v[112:115], v[184:187], v[172:175], v[112:115]
	s_bitcmp1_b32 s57, 0
	s_cselect_b32 s1, 0x12000, 0
	v_or_b32_e32 v172, s1, v196
	v_add_u32_e32 v172, v172, v200
	s_waitcnt vmcnt(3)
	ds_write_b128 v172, v[36:39]
	s_waitcnt vmcnt(2)
	ds_write_b128 v172, v[44:47] offset:9216
	s_waitcnt lgkmcnt(6)
	v_mfma_f32_16x16x32_bf16 v[108:111], v[176:179], v[164:167], v[108:111]
	v_mfma_f32_16x16x32_bf16 v[100:103], v[216:219], v[164:167], v[100:103]
	v_mfma_f32_16x16x32_bf16 v[104:107], v[188:191], v[164:167], v[104:107]
	v_mfma_f32_16x16x32_bf16 v[96:99], v[184:187], v[164:167], v[96:99]
	s_waitcnt vmcnt(1)
	ds_write_b128 v172, v[52:55] offset:18432
	s_waitcnt vmcnt(0)
	ds_write_b128 v172, v[60:63] offset:27648
	s_waitcnt lgkmcnt(7)
	v_mfma_f32_16x16x32_bf16 v[92:95], v[176:179], v[160:163], v[92:95]
	v_mfma_f32_16x16x32_bf16 v[84:87], v[216:219], v[160:163], v[84:87]
	v_mfma_f32_16x16x32_bf16 v[88:91], v[188:191], v[160:163], v[88:91]
	v_mfma_f32_16x16x32_bf16 v[80:83], v[184:187], v[160:163], v[80:83]
	ds_write_b128 v172, v[32:35] offset:36864
	ds_write_b128 v172, v[40:43] offset:46080
	s_waitcnt lgkmcnt(8)
	v_mfma_f32_16x16x32_bf16 v[76:79], v[176:179], v[180:183], v[76:79]
	v_mfma_f32_16x16x32_bf16 v[72:75], v[216:219], v[180:183], v[72:75]
	v_mfma_f32_16x16x32_bf16 v[68:71], v[188:191], v[180:183], v[68:71]
	v_mfma_f32_16x16x32_bf16 v[64:67], v[184:187], v[180:183], v[64:67]
	ds_write_b128 v172, v[48:51] offset:55296
	ds_write_b128 v172, v[56:59] offset:64512

; #define MFMA16(a, b, c) __builtin_amdgcn_mfma_f32_16x16x32_bf16((a), (b), (c), 0, 0, 0)
;     ...
;         const int h = gi % HG;
; #pragma unroll
;         for (int i = 0; i < FA; ++i)
; #pragma unroll
;           for (int j = 0; j < 4; ++j)
;             acc[h * FA + i][j] = NAT ? MFMA16(fa[gi & 1][i], fb[ks & 1][j], acc[h * FA + i][j]) : MFMA16(fb[ks & 1][j], fa[gi & 1][i], acc[h * FA + i][j]);
;         __builtin_amdgcn_sched_barrier(0);
;       }
;     }
;     if (kt == nk - 1) {
;       int mt, nt; tile_at(jt, mt, nt);
;       f(mt, nt, [&](auto&& a, auto&& bfn, auto&& ep) { ep(acc, wm, wn, lane); });
; #pragma unroll
;       for (int i = 0; i < MI; ++i)
; #pragma unroll
;         for (int j = 0; j < 4; ++j) acc[i][j] = (f32x4){0.f, 0.f, 0.f, 0.f};
;       kt = 0; ++jt;
;     } else ++kt;
.LBB0_2122:
	s_waitcnt lgkmcnt(9)
	v_mfma_f32_16x16x32_bf16 v[28:31], v[176:179], v[244:247], v[28:31]
	v_mfma_f32_16x16x32_bf16 v[20:23], v[216:219], v[244:247], v[20:23]
	v_mfma_f32_16x16x32_bf16 v[24:27], v[188:191], v[244:247], v[24:27]
	v_mfma_f32_16x16x32_bf16 v[16:19], v[184:187], v[244:247], v[16:19]
	s_waitcnt lgkmcnt(8)
	v_mfma_f32_16x16x32_bf16 v[12:15], v[176:179], v[168:171], v[12:15]
	v_mfma_f32_16x16x32_bf16 v[8:11], v[216:219], v[168:171], v[8:11]
	v_mfma_f32_16x16x32_bf16 v[4:7], v[188:191], v[168:171], v[4:7]
	v_mfma_f32_16x16x32_bf16 v[0:3], v[184:187], v[168:171], v[0:3]
	s_waitcnt lgkmcnt(0)
	s_cmp_lg_u32 s3, 15
	s_mov_b64 s[0:1], -1
	s_cbranch_scc0 .LBB0_2124
	s_add_i32 s3, s3, 1
	s_mov_b64 s[0:1], 0

; #define MFMA16(a, b, c) __builtin_amdgcn_mfma_f32_16x16x32_bf16((a), (b), (c), 0, 0, 0)
;     ...
;     bf16_t* sA = sm + (q & 1) * STG; bf16_t* sB = sA + BM * LDSS;
;     constexpr int FA = MI < 4 ? MI : 4, HG = MI / FA, NG = 2 * HG;
;     bf16x8 fb[2][4], fa[2][FA];
;     const bf16_t* pA = sA + (wm * MI * 16) * LDSS + fro; const bf16_t* pB = sB + (wn * 64) * LDSS + fro;
; #pragma unroll
;     for (int j = 0; j < 4; ++j) fb[0][j] = *(const bf16x8*)(pB + (j * 16) * LDSS);
; #pragma unroll
;     for (int i = 0; i < FA; ++i) fa[0][i] = *(const bf16x8*)(pA + (i * 16) * LDSS);
;     __builtin_amdgcn_sched_barrier(0);
;     if (q + 1 < Q) {
;       bf16_t* nA = sm + ((q + 1) & 1) * STG; bf16_t* nB = nA + BM * LDSS;
; #pragma unroll
;       for (int i = 0; i < AR; ++i) *(u32x4*)(nA + (lr + 64 * i) * LDSS + lc) = ra[i];
; #pragma unroll
;       for (int i = 0; i < BR; ++i) *(u32x4*)(nB + (lr + 64 * i) * LDSS + lc) = rb[i];
;     }
;     if (q + 2 < Q) {
;       int kt2 = kt + 2;
;       if (kt2 >= nk) { kt2 -= nk; if (kt2 == 0) set_offs(jt + 1); }
;       const char* gk = gb + kt2 * 128;
; #pragma unroll
;       for (int i = 0; i < AR; ++i) ra[i] = *(const u32x4*)(gk + ap[i]);
; #pragma unroll
;       for (int i = 0; i < BR; ++i) rb[i] = *(const u32x4*)(gk + bp[i]);
;     }
;     __builtin_amdgcn_sched_barrier(0);
;     {
; #pragma unroll
;       for (int gi = 0; gi < NG; ++gi) {
;         const int ks = gi / HG;
;         if (gi + 1 < NG) {
;           const int ks1 = (gi + 1) / HG, h1 = (gi + 1) % HG;
;           if (ks1 != ks) {
; #pragma unroll
;             for (int j = 0; j < 4; ++j) fb[ks1 & 1][j] = *(const bf16x8*)(pB + (j * 16) * LDSS + ks1 * 32);
;           }
; #pragma unroll
;           for (int i = 0; i < FA; ++i) fa[(gi + 1) & 1][i] = *(const bf16x8*)(pA + ((h1 * FA + i) * 16) * LDSS + ks1 * 32);
;         }
;         const int h = gi % HG;
; #pragma unroll
;         for (int i = 0; i < FA; ++i)
; #pragma unroll
;           for (int j = 0; j < 4; ++j)
;             acc[h * FA + i][j] = NAT ? MFMA16(fa[gi & 1][i], fb[ks & 1][j], acc[h * FA + i][j]) : MFMA16(fb[ks & 1][j], fa[gi & 1][i], acc[h * FA + i][j]);
;         __builtin_amdgcn_sched_barrier(0);
.LBB0_2252:
	s_bitcmp1_b32 s0, 0
	s_cselect_b32 s1, 0x12000, 0
	v_add3_u32 v246, s1, v237, v244
	v_add3_u32 v245, s1, v236, v244
	ds_read_b128 v[168:171], v246 offset:36864
	ds_read_b128 v[188:191], v245
	ds_read_b128 v[172:175], v246 offset:39168
	ds_read_b128 v[164:167], v246 offset:41472
	ds_read_b128 v[160:163], v246 offset:43776
	ds_read_b128 v[184:187], v245 offset:2304
	ds_read_b128 v[180:183], v245 offset:4608
	ds_read_b128 v[176:179], v245 offset:6912
	s_add_i32 s54, s0, 1
	s_waitcnt lgkmcnt(6)
	v_mfma_f32_16x16x32_bf16 v[156:159], v[168:171], v[188:191], v[156:159]
	s_waitcnt lgkmcnt(5)
	v_mfma_f32_16x16x32_bf16 v[152:155], v[172:175], v[188:191], v[152:155]
	s_waitcnt lgkmcnt(4)
	v_mfma_f32_16x16x32_bf16 v[148:151], v[164:167], v[188:191], v[148:151]
	s_waitcnt lgkmcnt(3)
	v_mfma_f32_16x16x32_bf16 v[144:147], v[160:163], v[188:191], v[144:147]
	ds_read_b128 v[216:219], v245 offset:9216
	ds_read_b128 v[188:191], v245 offset:11520
	s_waitcnt lgkmcnt(4)
	v_mfma_f32_16x16x32_bf16 v[140:143], v[168:171], v[184:187], v[140:143]
	v_mfma_f32_16x16x32_bf16 v[136:139], v[172:175], v[184:187], v[136:139]
	v_mfma_f32_16x16x32_bf16 v[132:135], v[164:167], v[184:187], v[132:135]
	v_mfma_f32_16x16x32_bf16 v[128:131], v[160:163], v[184:187], v[128:131]
	ds_read_b128 v[184:187], v245 offset:13824
	s_waitcnt lgkmcnt(4)
	v_mfma_f32_16x16x32_bf16 v[124:127], v[168:171], v[180:183], v[124:127]
	v_mfma_f32_16x16x32_bf16 v[120:123], v[172:175], v[180:183], v[120:123]
	v_mfma_f32_16x16x32_bf16 v[116:119], v[164:167], v[180:183], v[116:119]
	v_mfma_f32_16x16x32_bf16 v[112:115], v[160:163], v[180:183], v[112:115]
	ds_read_b128 v[180:183], v245 offset:16128
	s_waitcnt lgkmcnt(4)
	v_mfma_f32_16x16x32_bf16 v[108:111], v[168:171], v[176:179], v[108:111]
	v_mfma_f32_16x16x32_bf16 v[104:107], v[172:175], v[176:179], v[104:107]
	v_mfma_f32_16x16x32_bf16 v[100:103], v[164:167], v[176:179], v[100:103]
	v_mfma_f32_16x16x32_bf16 v[96:99], v[160:163], v[176:179], v[96:99]
	ds_read_b128 v[176:179], v246 offset:36928
	s_waitcnt lgkmcnt(4)
	v_mfma_f32_16x16x32_bf16 v[92:95], v[168:171], v[216:219], v[92:95]
	v_mfma_f32_16x16x32_bf16 v[88:91], v[172:175], v[216:219], v[88:91]
	v_mfma_f32_16x16x32_bf16 v[84:87], v[164:167], v[216:219], v[84:87]
	v_mfma_f32_16x16x32_bf16 v[80:83], v[160:163], v[216:219], v[80:83]
	ds_read_b128 v[216:219], v246 offset:39232
	s_waitcnt lgkmcnt(4)
	v_mfma_f32_16x16x32_bf16 v[76:79], v[168:171], v[188:191], v[76:79]
	v_mfma_f32_16x16x32_bf16 v[72:75], v[172:175], v[188:191], v[72:75]
	v_mfma_f32_16x16x32_bf16 v[68:71], v[164:167], v[188:191], v[68:71]
	v_mfma_f32_16x16x32_bf16 v[64:67], v[160:163], v[188:191], v[64:67]
	ds_read_b128 v[188:191], v246 offset:41536
	s_waitcnt lgkmcnt(4)
	v_mfma_f32_16x16x32_bf16 v[60:63], v[168:171], v[184:187], v[60:63]
	v_mfma_f32_16x16x32_bf16 v[56:59], v[172:175], v[184:187], v[56:59]
	v_mfma_f32_16x16x32_bf16 v[52:55], v[164:167], v[184:187], v[52:55]
	v_mfma_f32_16x16x32_bf16 v[48:51], v[160:163], v[184:187], v[48:51]
	ds_read_b128 v[184:187], v246 offset:43840
	ds_read_b128 v[246:249], v245 offset:64
	s_waitcnt lgkmcnt(5)
	v_mfma_f32_16x16x32_bf16 v[44:47], v[168:171], v[180:183], v[44:47]
	ds_read_b128 v[168:171], v245 offset:2368
	v_mfma_f32_16x16x32_bf16 v[40:43], v[172:175], v[180:183], v[40:43]
	ds_read_b128 v[172:175], v245 offset:4672
	v_mfma_f32_16x16x32_bf16 v[36:39], v[164:167], v[180:183], v[36:39]
	ds_read_b128 v[164:167], v245 offset:6976
	v_mfma_f32_16x16x32_bf16 v[32:35], v[160:163], v[180:183], v[32:35]
	ds_read_b128 v[160:163], v245 offset:9280
	ds_read_b128 v[180:183], v245 offset:11584
	s_waitcnt lgkmcnt(5)
	v_mfma_f32_16x16x32_bf16 v[156:159], v[176:179], v[246:249], v[156:159]
	v_mfma_f32_16x16x32_bf16 v[152:155], v[216:219], v[246:249], v[152:155]
	v_mfma_f32_16x16x32_bf16 v[148:151], v[188:191], v[246:249], v[148:151]
	v_mfma_f32_16x16x32_bf16 v[144:147], v[184:187], v[246:249], v[144:147]
	ds_read_b128 v[246:249], v245 offset:13888
	s_waitcnt lgkmcnt(5)
	v_mfma_f32_16x16x32_bf16 v[140:143], v[176:179], v[168:171], v[140:143]
	v_mfma_f32_16x16x32_bf16 v[136:139], v[216:219], v[168:171], v[136:139]
	v_mfma_f32_16x16x32_bf16 v[132:135], v[188:191], v[168:171], v[132:135]
	v_mfma_f32_16x16x32_bf16 v[128:131], v[184:187], v[168:171], v[128:131]
	ds_read_b128 v[168:171], v245 offset:16192
	s_waitcnt lgkmcnt(5)
	v_mfma_f32_16x16x32_bf16 v[124:127], v[176:179], v[172:175], v[124:127]
	v_mfma_f32_16x16x32_bf16 v[120:123], v[216:219], v[172:175], v[120:123]
	v_mfma_f32_16x16x32_bf16 v[116:119], v[188:191], v[172:175], v[116:119]
	v_mfma_f32_16x16x32_bf16 v[112:115], v[184:187], v[172:175], v[112:115]
	s_bitcmp1_b32 s54, 0
	s_cselect_b32 s1, 0x12000, 0
	v_or_b32_e32 v172, s1, v231
	v_add_u32_e32 v172, v172, v235
	s_waitcnt vmcnt(7)
	ds_write_b128 v172, v[0:3]
	s_waitcnt vmcnt(6)
	ds_write_b128 v172, v[4:7] offset:9216
	s_waitcnt lgkmcnt(6)
	v_mfma_f32_16x16x32_bf16 v[108:111], v[176:179], v[164:167], v[108:111]
	v_mfma_f32_16x16x32_bf16 v[104:107], v[216:219], v[164:167], v[104:107]
	v_mfma_f32_16x16x32_bf16 v[100:103], v[188:191], v[164:167], v[100:103]
	v_mfma_f32_16x16x32_bf16 v[96:99], v[184:187], v[164:167], v[96:99]
	s_waitcnt vmcnt(5)
	ds_write_b128 v172, v[8:11] offset:18432
	s_waitcnt vmcnt(4)
	ds_write_b128 v172, v[12:15] offset:27648
	s_waitcnt lgkmcnt(7)
	v_mfma_f32_16x16x32_bf16 v[92:95], v[176:179], v[160:163], v[92:95]
	v_mfma_f32_16x16x32_bf16 v[88:91], v[216:219], v[160:163], v[88:91]
	v_mfma_f32_16x16x32_bf16 v[84:87], v[188:191], v[160:163], v[84:87]
	v_mfma_f32_16x16x32_bf16 v[80:83], v[184:187], v[160:163], v[80:83]
	s_waitcnt vmcnt(3)
	ds_write_b128 v172, v[16:19] offset:36864
	s_waitcnt vmcnt(2)
	ds_write_b128 v172, v[20:23] offset:46080
	s_waitcnt lgkmcnt(8)
	v_mfma_f32_16x16x32_bf16 v[76:79], v[176:179], v[180:183], v[76:79]
	v_mfma_f32_16x16x32_bf16 v[72:75], v[216:219], v[180:183], v[72:75]
	v_mfma_f32_16x16x32_bf16 v[68:71], v[188:191], v[180:183], v[68:71]
	v_mfma_f32_16x16x32_bf16 v[64:67], v[184:187], v[180:183], v[64:67]
	s_waitcnt vmcnt(1)
	ds_write_b128 v172, v[24:27] offset:55296
	s_waitcnt vmcnt(0)
	ds_write_b128 v172, v[28:31] offset:64512

; #define MFMA16(a, b, c) __builtin_amdgcn_mfma_f32_16x16x32_bf16((a), (b), (c), 0, 0, 0)
;     ...
;         const int h = gi % HG;
; #pragma unroll
;         for (int i = 0; i < FA; ++i)
; #pragma unroll
;           for (int j = 0; j < 4; ++j)
;             acc[h * FA + i][j] = NAT ? MFMA16(fa[gi & 1][i], fb[ks & 1][j], acc[h * FA + i][j]) : MFMA16(fb[ks & 1][j], fa[gi & 1][i], acc[h * FA + i][j]);
;         __builtin_amdgcn_sched_barrier(0);
;       }
;     }
;     if (kt == nk - 1) {
;       int mt, nt; tile_at(jt, mt, nt);
;       f(mt, nt, [&](auto&& a, auto&& bfn, auto&& ep) { ep(acc, wm, wn, lane); });
; #pragma unroll
;       for (int i = 0; i < MI; ++i)
; #pragma unroll
;         for (int j = 0; j < 4; ++j) acc[i][j] = (f32x4){0.f, 0.f, 0.f, 0.f};
;       kt = 0; ++jt;
;     } else ++kt;
.LBB0_2264:
	s_waitcnt lgkmcnt(9)
	v_mfma_f32_16x16x32_bf16 v[60:63], v[176:179], v[246:249], v[60:63]
	v_mfma_f32_16x16x32_bf16 v[56:59], v[216:219], v[246:249], v[56:59]
	v_mfma_f32_16x16x32_bf16 v[52:55], v[188:191], v[246:249], v[52:55]
	v_mfma_f32_16x16x32_bf16 v[48:51], v[184:187], v[246:249], v[48:51]
	s_waitcnt lgkmcnt(8)
	v_mfma_f32_16x16x32_bf16 v[44:47], v[176:179], v[168:171], v[44:47]
	v_mfma_f32_16x16x32_bf16 v[40:43], v[216:219], v[168:171], v[40:43]
	v_mfma_f32_16x16x32_bf16 v[36:39], v[188:191], v[168:171], v[36:39]
	v_mfma_f32_16x16x32_bf16 v[32:35], v[184:187], v[168:171], v[32:35]
	s_waitcnt lgkmcnt(0)
	s_cmp_lg_u32 s55, 55
	s_mov_b64 s[0:1], -1
	s_cbranch_scc0 .LBB0_2266
	s_add_i32 s55, s55, 1
	s_mov_b64 s[0:1], 0

; #define MFMA16(a, b, c) __builtin_amdgcn_mfma_f32_16x16x32_bf16((a), (b), (c), 0, 0, 0)
;     ...
;     bf16_t* sA = sm + (q & 1) * STG; bf16_t* sB = sA + BM * LDSS;
;     constexpr int FA = MI < 4 ? MI : 4, HG = MI / FA, NG = 2 * HG;
;     bf16x8 fb[2][4], fa[2][FA];
;     const bf16_t* pA = sA + (wm * MI * 16) * LDSS + fro; const bf16_t* pB = sB + (wn * 64) * LDSS + fro;
; #pragma unroll
;     for (int j = 0; j < 4; ++j) fb[0][j] = *(const bf16x8*)(pB + (j * 16) * LDSS);
; #pragma unroll
;     for (int i = 0; i < FA; ++i) fa[0][i] = *(const bf16x8*)(pA + (i * 16) * LDSS);
;     __builtin_amdgcn_sched_barrier(0);
;     if (q + 1 < Q) {
;       bf16_t* nA = sm + ((q + 1) & 1) * STG; bf16_t* nB = nA + BM * LDSS;
; #pragma unroll
;       for (int i = 0; i < AR; ++i) *(u32x4*)(nA + (lr + 64 * i) * LDSS + lc) = ra[i];
; #pragma unroll
;       for (int i = 0; i < BR; ++i) *(u32x4*)(nB + (lr + 64 * i) * LDSS + lc) = rb[i];
;     }
;     if (q + 2 < Q) {
;       int kt2 = kt + 2;
;       if (kt2 >= nk) { kt2 -= nk; if (kt2 == 0) set_offs(jt + 1); }
;       const char* gk = gb + kt2 * 128;
; #pragma unroll
;       for (int i = 0; i < AR; ++i) ra[i] = *(const u32x4*)(gk + ap[i]);
; #pragma unroll
;       for (int i = 0; i < BR; ++i) rb[i] = *(const u32x4*)(gk + bp[i]);
;     }
;     __builtin_amdgcn_sched_barrier(0);
;     {
; #pragma unroll
;       for (int gi = 0; gi < NG; ++gi) {
;         const int ks = gi / HG;
;         if (gi + 1 < NG) {
;           const int ks1 = (gi + 1) / HG, h1 = (gi + 1) % HG;
;           if (ks1 != ks) {
; #pragma unroll
;             for (int j = 0; j < 4; ++j) fb[ks1 & 1][j] = *(const bf16x8*)(pB + (j * 16) * LDSS + ks1 * 32);
;           }
; #pragma unroll
;           for (int i = 0; i < FA; ++i) fa[(gi + 1) & 1][i] = *(const bf16x8*)(pA + ((h1 * FA + i) * 16) * LDSS + ks1 * 32);
;         }
;         const int h = gi % HG;
; #pragma unroll
;         for (int i = 0; i < FA; ++i)
; #pragma unroll
;           for (int j = 0; j < 4; ++j)
;             acc[h * FA + i][j] = NAT ? MFMA16(fa[gi & 1][i], fb[ks & 1][j], acc[h * FA + i][j]) : MFMA16(fb[ks & 1][j], fa[gi & 1][i], acc[h * FA + i][j]);
;         __builtin_amdgcn_sched_barrier(0);
.LBB0_2331:
	s_bitcmp1_b32 s0, 0
	s_cselect_b32 s1, 0x12000, 0
	v_add3_u32 v246, s1, v237, v244
	v_add3_u32 v245, s1, v236, v244
	ds_read_b128 v[168:171], v246 offset:36864
	ds_read_b128 v[188:191], v245
	ds_read_b128 v[172:175], v246 offset:39168
	ds_read_b128 v[164:167], v246 offset:41472
	ds_read_b128 v[160:163], v246 offset:43776
	ds_read_b128 v[184:187], v245 offset:2304
	ds_read_b128 v[180:183], v245 offset:4608
	ds_read_b128 v[176:179], v245 offset:6912
	s_add_i32 s55, s0, 1
	s_waitcnt lgkmcnt(6)
	v_mfma_f32_16x16x32_bf16 v[156:159], v[168:171], v[188:191], v[156:159]
	s_waitcnt lgkmcnt(5)
	v_mfma_f32_16x16x32_bf16 v[152:155], v[172:175], v[188:191], v[152:155]
	s_waitcnt lgkmcnt(4)
	v_mfma_f32_16x16x32_bf16 v[148:151], v[164:167], v[188:191], v[148:151]
	s_waitcnt lgkmcnt(3)
	v_mfma_f32_16x16x32_bf16 v[144:147], v[160:163], v[188:191], v[144:147]
	ds_read_b128 v[216:219], v245 offset:9216
	ds_read_b128 v[188:191], v245 offset:11520
	s_waitcnt lgkmcnt(4)
	v_mfma_f32_16x16x32_bf16 v[140:143], v[168:171], v[184:187], v[140:143]
	v_mfma_f32_16x16x32_bf16 v[136:139], v[172:175], v[184:187], v[136:139]
	v_mfma_f32_16x16x32_bf16 v[132:135], v[164:167], v[184:187], v[132:135]
	v_mfma_f32_16x16x32_bf16 v[128:131], v[160:163], v[184:187], v[128:131]
	ds_read_b128 v[184:187], v245 offset:13824
	s_waitcnt lgkmcnt(4)
	v_mfma_f32_16x16x32_bf16 v[124:127], v[168:171], v[180:183], v[124:127]
	v_mfma_f32_16x16x32_bf16 v[120:123], v[172:175], v[180:183], v[120:123]
	v_mfma_f32_16x16x32_bf16 v[116:119], v[164:167], v[180:183], v[116:119]
	v_mfma_f32_16x16x32_bf16 v[112:115], v[160:163], v[180:183], v[112:115]
	ds_read_b128 v[180:183], v245 offset:16128
	s_waitcnt lgkmcnt(4)
	v_mfma_f32_16x16x32_bf16 v[108:111], v[168:171], v[176:179], v[108:111]
	v_mfma_f32_16x16x32_bf16 v[104:107], v[172:175], v[176:179], v[104:107]
	v_mfma_f32_16x16x32_bf16 v[100:103], v[164:167], v[176:179], v[100:103]
	v_mfma_f32_16x16x32_bf16 v[96:99], v[160:163], v[176:179], v[96:99]
	ds_read_b128 v[176:179], v246 offset:36928
	s_waitcnt lgkmcnt(4)
	v_mfma_f32_16x16x32_bf16 v[92:95], v[168:171], v[216:219], v[92:95]
	v_mfma_f32_16x16x32_bf16 v[88:91], v[172:175], v[216:219], v[88:91]
	v_mfma_f32_16x16x32_bf16 v[84:87], v[164:167], v[216:219], v[84:87]
	v_mfma_f32_16x16x32_bf16 v[80:83], v[160:163], v[216:219], v[80:83]
	ds_read_b128 v[216:219], v246 offset:39232
	s_waitcnt lgkmcnt(4)
	v_mfma_f32_16x16x32_bf16 v[76:79], v[168:171], v[188:191], v[76:79]
	v_mfma_f32_16x16x32_bf16 v[72:75], v[172:175], v[188:191], v[72:75]
	v_mfma_f32_16x16x32_bf16 v[68:71], v[164:167], v[188:191], v[68:71]
	v_mfma_f32_16x16x32_bf16 v[64:67], v[160:163], v[188:191], v[64:67]
	ds_read_b128 v[188:191], v246 offset:41536
	s_waitcnt lgkmcnt(4)
	v_mfma_f32_16x16x32_bf16 v[60:63], v[168:171], v[184:187], v[60:63]
	v_mfma_f32_16x16x32_bf16 v[56:59], v[172:175], v[184:187], v[56:59]
	v_mfma_f32_16x16x32_bf16 v[52:55], v[164:167], v[184:187], v[52:55]
	v_mfma_f32_16x16x32_bf16 v[48:51], v[160:163], v[184:187], v[48:51]
	ds_read_b128 v[184:187], v246 offset:43840
	ds_read_b128 v[246:249], v245 offset:64
	s_waitcnt lgkmcnt(5)
	v_mfma_f32_16x16x32_bf16 v[44:47], v[168:171], v[180:183], v[44:47]
	ds_read_b128 v[168:171], v245 offset:2368
	v_mfma_f32_16x16x32_bf16 v[40:43], v[172:175], v[180:183], v[40:43]
	ds_read_b128 v[172:175], v245 offset:4672
	v_mfma_f32_16x16x32_bf16 v[36:39], v[164:167], v[180:183], v[36:39]
	ds_read_b128 v[164:167], v245 offset:6976
	v_mfma_f32_16x16x32_bf16 v[32:35], v[160:163], v[180:183], v[32:35]
	ds_read_b128 v[160:163], v245 offset:9280
	ds_read_b128 v[180:183], v245 offset:11584
	s_waitcnt lgkmcnt(5)
	v_mfma_f32_16x16x32_bf16 v[156:159], v[176:179], v[246:249], v[156:159]
	v_mfma_f32_16x16x32_bf16 v[152:155], v[216:219], v[246:249], v[152:155]
	v_mfma_f32_16x16x32_bf16 v[148:151], v[188:191], v[246:249], v[148:151]
	v_mfma_f32_16x16x32_bf16 v[144:147], v[184:187], v[246:249], v[144:147]
	ds_read_b128 v[246:249], v245 offset:13888
	s_waitcnt lgkmcnt(5)
	v_mfma_f32_16x16x32_bf16 v[140:143], v[176:179], v[168:171], v[140:143]
	v_mfma_f32_16x16x32_bf16 v[136:139], v[216:219], v[168:171], v[136:139]
	v_mfma_f32_16x16x32_bf16 v[132:135], v[188:191], v[168:171], v[132:135]
	v_mfma_f32_16x16x32_bf16 v[128:131], v[184:187], v[168:171], v[128:131]
	ds_read_b128 v[168:171], v245 offset:16192
	s_waitcnt lgkmcnt(5)
	v_mfma_f32_16x16x32_bf16 v[124:127], v[176:179], v[172:175], v[124:127]
	v_mfma_f32_16x16x32_bf16 v[120:123], v[216:219], v[172:175], v[120:123]
	v_mfma_f32_16x16x32_bf16 v[116:119], v[188:191], v[172:175], v[116:119]
	v_mfma_f32_16x16x32_bf16 v[112:115], v[184:187], v[172:175], v[112:115]
	s_bitcmp1_b32 s55, 0
	s_cselect_b32 s1, 0x12000, 0
	v_or_b32_e32 v172, s1, v231
	v_add_u32_e32 v172, v172, v235
	s_waitcnt vmcnt(7)
	ds_write_b128 v172, v[0:3]
	s_waitcnt vmcnt(6)
	ds_write_b128 v172, v[4:7] offset:9216
	s_waitcnt lgkmcnt(6)
	v_mfma_f32_16x16x32_bf16 v[108:111], v[176:179], v[164:167], v[108:111]
	v_mfma_f32_16x16x32_bf16 v[104:107], v[216:219], v[164:167], v[104:107]
	v_mfma_f32_16x16x32_bf16 v[100:103], v[188:191], v[164:167], v[100:103]
	v_mfma_f32_16x16x32_bf16 v[96:99], v[184:187], v[164:167], v[96:99]
	s_waitcnt vmcnt(5)
	ds_write_b128 v172, v[8:11] offset:18432
	s_waitcnt vmcnt(4)
	ds_write_b128 v172, v[12:15] offset:27648
	s_waitcnt lgkmcnt(7)
	v_mfma_f32_16x16x32_bf16 v[92:95], v[176:179], v[160:163], v[92:95]
	v_mfma_f32_16x16x32_bf16 v[88:91], v[216:219], v[160:163], v[88:91]
	v_mfma_f32_16x16x32_bf16 v[84:87], v[188:191], v[160:163], v[84:87]
	v_mfma_f32_16x16x32_bf16 v[80:83], v[184:187], v[160:163], v[80:83]
	s_waitcnt vmcnt(3)
	ds_write_b128 v172, v[16:19] offset:36864
	s_waitcnt vmcnt(2)
	ds_write_b128 v172, v[20:23] offset:46080
	s_waitcnt lgkmcnt(8)
	v_mfma_f32_16x16x32_bf16 v[76:79], v[176:179], v[180:183], v[76:79]
	v_mfma_f32_16x16x32_bf16 v[72:75], v[216:219], v[180:183], v[72:75]
	v_mfma_f32_16x16x32_bf16 v[68:71], v[188:191], v[180:183], v[68:71]
	v_mfma_f32_16x16x32_bf16 v[64:67], v[184:187], v[180:183], v[64:67]
	s_waitcnt vmcnt(1)
	ds_write_b128 v172, v[24:27] offset:55296
	s_waitcnt vmcnt(0)
	ds_write_b128 v172, v[28:31] offset:64512

; #define MFMA16(a, b, c) __builtin_amdgcn_mfma_f32_16x16x32_bf16((a), (b), (c), 0, 0, 0)
;     ...
;         const int h = gi % HG;
; #pragma unroll
;         for (int i = 0; i < FA; ++i)
; #pragma unroll
;           for (int j = 0; j < 4; ++j)
;             acc[h * FA + i][j] = NAT ? MFMA16(fa[gi & 1][i], fb[ks & 1][j], acc[h * FA + i][j]) : MFMA16(fb[ks & 1][j], fa[gi & 1][i], acc[h * FA + i][j]);
;         __builtin_amdgcn_sched_barrier(0);
;       }
;     }
;     if (kt == nk - 1) {
;       int mt, nt; tile_at(jt, mt, nt);
;       f(mt, nt, [&](auto&& a, auto&& bfn, auto&& ep) { ep(acc, wm, wn, lane); });
; #pragma unroll
;       for (int i = 0; i < MI; ++i)
; #pragma unroll
;         for (int j = 0; j < 4; ++j) acc[i][j] = (f32x4){0.f, 0.f, 0.f, 0.f};
;       kt = 0; ++jt;
;     } else ++kt;
.LBB0_2343:
	s_waitcnt lgkmcnt(9)
	v_mfma_f32_16x16x32_bf16 v[60:63], v[176:179], v[246:249], v[60:63]
	v_mfma_f32_16x16x32_bf16 v[56:59], v[216:219], v[246:249], v[56:59]
	v_mfma_f32_16x16x32_bf16 v[52:55], v[188:191], v[246:249], v[52:55]
	v_mfma_f32_16x16x32_bf16 v[48:51], v[184:187], v[246:249], v[48:51]
	s_waitcnt lgkmcnt(8)
	v_mfma_f32_16x16x32_bf16 v[44:47], v[176:179], v[168:171], v[44:47]
	v_mfma_f32_16x16x32_bf16 v[40:43], v[216:219], v[168:171], v[40:43]
	v_mfma_f32_16x16x32_bf16 v[36:39], v[188:191], v[168:171], v[36:39]
	v_mfma_f32_16x16x32_bf16 v[32:35], v[184:187], v[168:171], v[32:35]
	s_waitcnt lgkmcnt(0)
	s_cmp_lg_u32 s56, 55
	s_mov_b64 s[0:1], -1
	s_cbranch_scc0 .LBB0_2345
	s_add_i32 s56, s56, 1
	s_mov_b64 s[0:1], 0

; #define MFMA16(a, b, c) __builtin_amdgcn_mfma_f32_16x16x32_bf16((a), (b), (c), 0, 0, 0)
;     ...
;     bf16_t* sA = sm + (q & 1) * STG; bf16_t* sB = sA + BM * LDSS;
;     constexpr int FA = MI < 4 ? MI : 4, HG = MI / FA, NG = 2 * HG;
;     bf16x8 fb[2][4], fa[2][FA];
;     const bf16_t* pA = sA + (wm * MI * 16) * LDSS + fro; const bf16_t* pB = sB + (wn * 64) * LDSS + fro;
; #pragma unroll
;     for (int j = 0; j < 4; ++j) fb[0][j] = *(const bf16x8*)(pB + (j * 16) * LDSS);
; #pragma unroll
;     for (int i = 0; i < FA; ++i) fa[0][i] = *(const bf16x8*)(pA + (i * 16) * LDSS);
;     __builtin_amdgcn_sched_barrier(0);
;     if (q + 1 < Q) {
;       bf16_t* nA = sm + ((q + 1) & 1) * STG; bf16_t* nB = nA + BM * LDSS;
; #pragma unroll
;       for (int i = 0; i < AR; ++i) *(u32x4*)(nA + (lr + 64 * i) * LDSS + lc) = ra[i];
; #pragma unroll
;       for (int i = 0; i < BR; ++i) *(u32x4*)(nB + (lr + 64 * i) * LDSS + lc) = rb[i];
;     }
;     if (q + 2 < Q) {
;       int kt2 = kt + 2;
;       if (kt2 >= nk) { kt2 -= nk; if (kt2 == 0) set_offs(jt + 1); }
;       const char* gk = gb + kt2 * 128;
; #pragma unroll
;       for (int i = 0; i < AR; ++i) ra[i] = *(const u32x4*)(gk + ap[i]);
; #pragma unroll
;       for (int i = 0; i < BR; ++i) rb[i] = *(const u32x4*)(gk + bp[i]);
;     }
;     __builtin_amdgcn_sched_barrier(0);
;     {
; #pragma unroll
;       for (int gi = 0; gi < NG; ++gi) {
;         const int ks = gi / HG;
;         if (gi + 1 < NG) {
;           const int ks1 = (gi + 1) / HG, h1 = (gi + 1) % HG;
;           if (ks1 != ks) {
; #pragma unroll
;             for (int j = 0; j < 4; ++j) fb[ks1 & 1][j] = *(const bf16x8*)(pB + (j * 16) * LDSS + ks1 * 32);
;           }
; #pragma unroll
;           for (int i = 0; i < FA; ++i) fa[(gi + 1) & 1][i] = *(const bf16x8*)(pA + ((h1 * FA + i) * 16) * LDSS + ks1 * 32);
;         }
;         const int h = gi % HG;
; #pragma unroll
;         for (int i = 0; i < FA; ++i)
; #pragma unroll
;           for (int j = 0; j < 4; ++j)
;             acc[h * FA + i][j] = NAT ? MFMA16(fa[gi & 1][i], fb[ks & 1][j], acc[h * FA + i][j]) : MFMA16(fb[ks & 1][j], fa[gi & 1][i], acc[h * FA + i][j]);
;         __builtin_amdgcn_sched_barrier(0);
.LBB0_2494:
	s_bitcmp1_b32 s0, 0
	s_cselect_b32 s1, 0x12000, 0
	v_add3_u32 v243, s1, v235, v239
	v_add3_u32 v242, s1, v234, v239
	ds_read_b128 v[168:171], v243 offset:36864
	ds_read_b128 v[188:191], v242
	ds_read_b128 v[172:175], v243 offset:39168
	ds_read_b128 v[164:167], v243 offset:41472
	ds_read_b128 v[160:163], v243 offset:43776
	ds_read_b128 v[184:187], v242 offset:2304
	ds_read_b128 v[180:183], v242 offset:4608
	ds_read_b128 v[176:179], v242 offset:6912
	s_add_i32 s30, s0, 1
	s_waitcnt lgkmcnt(6)
	v_mfma_f32_16x16x32_bf16 v[156:159], v[168:171], v[188:191], v[156:159]
	s_waitcnt lgkmcnt(5)
	v_mfma_f32_16x16x32_bf16 v[148:151], v[172:175], v[188:191], v[148:151]
	s_waitcnt lgkmcnt(4)
	v_mfma_f32_16x16x32_bf16 v[152:155], v[164:167], v[188:191], v[152:155]
	s_waitcnt lgkmcnt(3)
	v_mfma_f32_16x16x32_bf16 v[144:147], v[160:163], v[188:191], v[144:147]
	ds_read_b128 v[216:219], v242 offset:9216
	ds_read_b128 v[188:191], v242 offset:11520
	s_waitcnt lgkmcnt(4)
	v_mfma_f32_16x16x32_bf16 v[140:143], v[168:171], v[184:187], v[140:143]
	v_mfma_f32_16x16x32_bf16 v[132:135], v[172:175], v[184:187], v[132:135]
	v_mfma_f32_16x16x32_bf16 v[136:139], v[164:167], v[184:187], v[136:139]
	v_mfma_f32_16x16x32_bf16 v[128:131], v[160:163], v[184:187], v[128:131]
	ds_read_b128 v[184:187], v242 offset:13824
	s_waitcnt lgkmcnt(4)
	v_mfma_f32_16x16x32_bf16 v[124:127], v[168:171], v[180:183], v[124:127]
	v_mfma_f32_16x16x32_bf16 v[116:119], v[172:175], v[180:183], v[116:119]
	v_mfma_f32_16x16x32_bf16 v[120:123], v[164:167], v[180:183], v[120:123]
	v_mfma_f32_16x16x32_bf16 v[112:115], v[160:163], v[180:183], v[112:115]
	ds_read_b128 v[180:183], v242 offset:16128
	s_waitcnt lgkmcnt(4)
	v_mfma_f32_16x16x32_bf16 v[108:111], v[168:171], v[176:179], v[108:111]
	v_mfma_f32_16x16x32_bf16 v[100:103], v[172:175], v[176:179], v[100:103]
	v_mfma_f32_16x16x32_bf16 v[104:107], v[164:167], v[176:179], v[104:107]
	v_mfma_f32_16x16x32_bf16 v[96:99], v[160:163], v[176:179], v[96:99]
	ds_read_b128 v[176:179], v243 offset:36928
	s_waitcnt lgkmcnt(4)
	v_mfma_f32_16x16x32_bf16 v[92:95], v[168:171], v[216:219], v[92:95]
	v_mfma_f32_16x16x32_bf16 v[84:87], v[172:175], v[216:219], v[84:87]
	v_mfma_f32_16x16x32_bf16 v[88:91], v[164:167], v[216:219], v[88:91]
	v_mfma_f32_16x16x32_bf16 v[80:83], v[160:163], v[216:219], v[80:83]
	ds_read_b128 v[216:219], v243 offset:39232
	s_waitcnt lgkmcnt(4)
	v_mfma_f32_16x16x32_bf16 v[76:79], v[168:171], v[188:191], v[76:79]
	v_mfma_f32_16x16x32_bf16 v[68:71], v[172:175], v[188:191], v[68:71]
	v_mfma_f32_16x16x32_bf16 v[72:75], v[164:167], v[188:191], v[72:75]
	v_mfma_f32_16x16x32_bf16 v[64:67], v[160:163], v[188:191], v[64:67]
	ds_read_b128 v[188:191], v243 offset:41536
	s_waitcnt lgkmcnt(4)
	v_mfma_f32_16x16x32_bf16 v[60:63], v[168:171], v[184:187], v[60:63]
	v_mfma_f32_16x16x32_bf16 v[52:55], v[172:175], v[184:187], v[52:55]
	v_mfma_f32_16x16x32_bf16 v[56:59], v[164:167], v[184:187], v[56:59]
	v_mfma_f32_16x16x32_bf16 v[48:51], v[160:163], v[184:187], v[48:51]
	ds_read_b128 v[184:187], v243 offset:43840
	ds_read_b128 v[244:247], v242 offset:64
	s_waitcnt lgkmcnt(5)
	v_mfma_f32_16x16x32_bf16 v[44:47], v[168:171], v[180:183], v[44:47]
	ds_read_b128 v[168:171], v242 offset:2368
	v_mfma_f32_16x16x32_bf16 v[36:39], v[172:175], v[180:183], v[36:39]
	ds_read_b128 v[172:175], v242 offset:4672
	v_mfma_f32_16x16x32_bf16 v[40:43], v[164:167], v[180:183], v[40:43]
	ds_read_b128 v[164:167], v242 offset:6976
	v_mfma_f32_16x16x32_bf16 v[32:35], v[160:163], v[180:183], v[32:35]
	ds_read_b128 v[160:163], v242 offset:9280
	ds_read_b128 v[180:183], v242 offset:11584
	s_waitcnt lgkmcnt(5)
	v_mfma_f32_16x16x32_bf16 v[156:159], v[176:179], v[244:247], v[156:159]
	v_mfma_f32_16x16x32_bf16 v[148:151], v[216:219], v[244:247], v[148:151]
	v_mfma_f32_16x16x32_bf16 v[152:155], v[188:191], v[244:247], v[152:155]
	v_mfma_f32_16x16x32_bf16 v[144:147], v[184:187], v[244:247], v[144:147]
	ds_read_b128 v[244:247], v242 offset:13888
	s_waitcnt lgkmcnt(5)
	v_mfma_f32_16x16x32_bf16 v[140:143], v[176:179], v[168:171], v[140:143]
	v_mfma_f32_16x16x32_bf16 v[132:135], v[216:219], v[168:171], v[132:135]
	v_mfma_f32_16x16x32_bf16 v[136:139], v[188:191], v[168:171], v[136:139]
	v_mfma_f32_16x16x32_bf16 v[128:131], v[184:187], v[168:171], v[128:131]
	ds_read_b128 v[168:171], v242 offset:16192
	s_waitcnt lgkmcnt(5)
	v_mfma_f32_16x16x32_bf16 v[124:127], v[176:179], v[172:175], v[124:127]
	v_mfma_f32_16x16x32_bf16 v[116:119], v[216:219], v[172:175], v[116:119]
	v_mfma_f32_16x16x32_bf16 v[120:123], v[188:191], v[172:175], v[120:123]
	v_mfma_f32_16x16x32_bf16 v[112:115], v[184:187], v[172:175], v[112:115]
	s_bitcmp1_b32 s30, 0
	s_cselect_b32 s1, 0x12000, 0
	v_or_b32_e32 v172, s1, v194
	v_add_u32_e32 v172, v172, v202
	s_waitcnt vmcnt(7)
	ds_write_b128 v172, v[0:3]
	s_waitcnt vmcnt(6)
	ds_write_b128 v172, v[4:7] offset:9216
	s_waitcnt lgkmcnt(6)
	v_mfma_f32_16x16x32_bf16 v[108:111], v[176:179], v[164:167], v[108:111]
	v_mfma_f32_16x16x32_bf16 v[100:103], v[216:219], v[164:167], v[100:103]
	v_mfma_f32_16x16x32_bf16 v[104:107], v[188:191], v[164:167], v[104:107]
	v_mfma_f32_16x16x32_bf16 v[96:99], v[184:187], v[164:167], v[96:99]
	s_waitcnt vmcnt(5)
	ds_write_b128 v172, v[8:11] offset:18432
	s_waitcnt vmcnt(4)
	ds_write_b128 v172, v[12:15] offset:27648
	s_waitcnt lgkmcnt(7)
	v_mfma_f32_16x16x32_bf16 v[92:95], v[176:179], v[160:163], v[92:95]
	v_mfma_f32_16x16x32_bf16 v[84:87], v[216:219], v[160:163], v[84:87]
	v_mfma_f32_16x16x32_bf16 v[88:91], v[188:191], v[160:163], v[88:91]
	v_mfma_f32_16x16x32_bf16 v[80:83], v[184:187], v[160:163], v[80:83]
	s_waitcnt vmcnt(3)
	ds_write_b128 v172, v[16:19] offset:36864
	s_waitcnt vmcnt(2)
	ds_write_b128 v172, v[20:23] offset:46080
	s_waitcnt lgkmcnt(8)
	v_mfma_f32_16x16x32_bf16 v[76:79], v[176:179], v[180:183], v[76:79]
	v_mfma_f32_16x16x32_bf16 v[68:71], v[216:219], v[180:183], v[68:71]
	v_mfma_f32_16x16x32_bf16 v[72:75], v[188:191], v[180:183], v[72:75]
	v_mfma_f32_16x16x32_bf16 v[64:67], v[184:187], v[180:183], v[64:67]
	s_waitcnt vmcnt(1)
	ds_write_b128 v172, v[24:27] offset:55296
	s_waitcnt vmcnt(0)
	ds_write_b128 v172, v[28:31] offset:64512

; #define MFMA16(a, b, c) __builtin_amdgcn_mfma_f32_16x16x32_bf16((a), (b), (c), 0, 0, 0)
;     ...
;         const int h = gi % HG;
; #pragma unroll
;         for (int i = 0; i < FA; ++i)
; #pragma unroll
;           for (int j = 0; j < 4; ++j)
;             acc[h * FA + i][j] = NAT ? MFMA16(fa[gi & 1][i], fb[ks & 1][j], acc[h * FA + i][j]) : MFMA16(fb[ks & 1][j], fa[gi & 1][i], acc[h * FA + i][j]);
;         __builtin_amdgcn_sched_barrier(0);
;       }
;     }
;     if (kt == nk - 1) {
;       int mt, nt; tile_at(jt, mt, nt);
;       f(mt, nt, [&](auto&& a, auto&& bfn, auto&& ep) { ep(acc, wm, wn, lane); });
; #pragma unroll
;       for (int i = 0; i < MI; ++i)
; #pragma unroll
;         for (int j = 0; j < 4; ++j) acc[i][j] = (f32x4){0.f, 0.f, 0.f, 0.f};
;       kt = 0; ++jt;
;     } else ++kt;
.LBB0_2506:
	s_waitcnt lgkmcnt(9)
	v_mfma_f32_16x16x32_bf16 v[60:63], v[176:179], v[244:247], v[60:63]
	v_mfma_f32_16x16x32_bf16 v[52:55], v[216:219], v[244:247], v[52:55]
	v_mfma_f32_16x16x32_bf16 v[56:59], v[188:191], v[244:247], v[56:59]
	v_mfma_f32_16x16x32_bf16 v[48:51], v[184:187], v[244:247], v[48:51]
	s_waitcnt lgkmcnt(8)
	v_mfma_f32_16x16x32_bf16 v[44:47], v[176:179], v[168:171], v[44:47]
	v_mfma_f32_16x16x32_bf16 v[36:39], v[216:219], v[168:171], v[36:39]
	v_mfma_f32_16x16x32_bf16 v[40:43], v[188:191], v[168:171], v[40:43]
	v_mfma_f32_16x16x32_bf16 v[32:35], v[184:187], v[168:171], v[32:35]
	s_waitcnt lgkmcnt(0)
	s_cmp_lg_u32 s31, 15
	s_mov_b64 s[0:1], -1
	s_cbranch_scc0 .LBB0_2508
	s_add_i32 s31, s31, 1
	s_mov_b64 s[0:1], 0

; #define MFMA16(a, b, c) __builtin_amdgcn_mfma_f32_16x16x32_bf16((a), (b), (c), 0, 0, 0)
;     ...
;     bf16_t* sA = sm + (q & 1) * STG; bf16_t* sB = sA + BM * LDSS;
;     constexpr int FA = MI < 4 ? MI : 4, HG = MI / FA, NG = 2 * HG;
;     bf16x8 fb[2][4], fa[2][FA];
;     const bf16_t* pA = sA + (wm * MI * 16) * LDSS + fro; const bf16_t* pB = sB + (wn * 64) * LDSS + fro;
; #pragma unroll
;     for (int j = 0; j < 4; ++j) fb[0][j] = *(const bf16x8*)(pB + (j * 16) * LDSS);
; #pragma unroll
;     for (int i = 0; i < FA; ++i) fa[0][i] = *(const bf16x8*)(pA + (i * 16) * LDSS);
;     __builtin_amdgcn_sched_barrier(0);
;     if (q + 1 < Q) {
;       bf16_t* nA = sm + ((q + 1) & 1) * STG; bf16_t* nB = nA + BM * LDSS;
; #pragma unroll
;       for (int i = 0; i < AR; ++i) *(u32x4*)(nA + (lr + 64 * i) * LDSS + lc) = ra[i];
; #pragma unroll
;       for (int i = 0; i < BR; ++i) *(u32x4*)(nB + (lr + 64 * i) * LDSS + lc) = rb[i];
;     }
;     if (q + 2 < Q) {
;       int kt2 = kt + 2;
;       if (kt2 >= nk) { kt2 -= nk; if (kt2 == 0) set_offs(jt + 1); }
;       const char* gk = gb + kt2 * 128;
; #pragma unroll
;       for (int i = 0; i < AR; ++i) ra[i] = *(const u32x4*)(gk + ap[i]);
; #pragma unroll
;       for (int i = 0; i < BR; ++i) rb[i] = *(const u32x4*)(gk + bp[i]);
;     }
;     __builtin_amdgcn_sched_barrier(0);
;     {
; #pragma unroll
;       for (int gi = 0; gi < NG; ++gi) {
;         const int ks = gi / HG;
;         if (gi + 1 < NG) {
;           const int ks1 = (gi + 1) / HG, h1 = (gi + 1) % HG;
;           if (ks1 != ks) {
; #pragma unroll
;             for (int j = 0; j < 4; ++j) fb[ks1 & 1][j] = *(const bf16x8*)(pB + (j * 16) * LDSS + ks1 * 32);
;           }
; #pragma unroll
;           for (int i = 0; i < FA; ++i) fa[(gi + 1) & 1][i] = *(const bf16x8*)(pA + ((h1 * FA + i) * 16) * LDSS + ks1 * 32);
;         }
;         const int h = gi % HG;
; #pragma unroll
;         for (int i = 0; i < FA; ++i)
; #pragma unroll
;           for (int j = 0; j < 4; ++j)
;             acc[h * FA + i][j] = NAT ? MFMA16(fa[gi & 1][i], fb[ks & 1][j], acc[h * FA + i][j]) : MFMA16(fb[ks & 1][j], fa[gi & 1][i], acc[h * FA + i][j]);
;         __builtin_amdgcn_sched_barrier(0);
.LBB0_2631:
	s_bitcmp1_b32 s0, 0
	s_cselect_b32 s1, 0x12000, 0
	v_add3_u32 v242, s1, v238, v241
	v_add3_u32 v192, s1, v237, v241
	ds_read_b128 v[168:171], v242 offset:36864
	ds_read_b128 v[188:191], v192
	ds_read_b128 v[172:175], v242 offset:39168
	ds_read_b128 v[164:167], v242 offset:41472
	ds_read_b128 v[160:163], v242 offset:43776
	ds_read_b128 v[184:187], v192 offset:2304
	ds_read_b128 v[180:183], v192 offset:4608
	ds_read_b128 v[176:179], v192 offset:6912
	s_add_i32 s38, s0, 1
	s_waitcnt lgkmcnt(6)
	v_mfma_f32_16x16x32_bf16 v[156:159], v[168:171], v[188:191], v[156:159]
	s_waitcnt lgkmcnt(5)
	v_mfma_f32_16x16x32_bf16 v[152:155], v[172:175], v[188:191], v[152:155]
	s_waitcnt lgkmcnt(4)
	v_mfma_f32_16x16x32_bf16 v[148:151], v[164:167], v[188:191], v[148:151]
	s_waitcnt lgkmcnt(3)
	v_mfma_f32_16x16x32_bf16 v[144:147], v[160:163], v[188:191], v[144:147]
	ds_read_b128 v[216:219], v192 offset:9216
	ds_read_b128 v[188:191], v192 offset:11520
	s_waitcnt lgkmcnt(4)
	v_mfma_f32_16x16x32_bf16 v[140:143], v[168:171], v[184:187], v[140:143]
	v_mfma_f32_16x16x32_bf16 v[136:139], v[172:175], v[184:187], v[136:139]
	v_mfma_f32_16x16x32_bf16 v[132:135], v[164:167], v[184:187], v[132:135]
	v_mfma_f32_16x16x32_bf16 v[128:131], v[160:163], v[184:187], v[128:131]
	ds_read_b128 v[184:187], v192 offset:13824
	s_waitcnt lgkmcnt(4)
	v_mfma_f32_16x16x32_bf16 v[124:127], v[168:171], v[180:183], v[124:127]
	v_mfma_f32_16x16x32_bf16 v[120:123], v[172:175], v[180:183], v[120:123]
	v_mfma_f32_16x16x32_bf16 v[116:119], v[164:167], v[180:183], v[116:119]
	v_mfma_f32_16x16x32_bf16 v[112:115], v[160:163], v[180:183], v[112:115]
	ds_read_b128 v[180:183], v192 offset:16128
	s_waitcnt lgkmcnt(4)
	v_mfma_f32_16x16x32_bf16 v[108:111], v[168:171], v[176:179], v[108:111]
	v_mfma_f32_16x16x32_bf16 v[104:107], v[172:175], v[176:179], v[104:107]
	v_mfma_f32_16x16x32_bf16 v[100:103], v[164:167], v[176:179], v[100:103]
	v_mfma_f32_16x16x32_bf16 v[96:99], v[160:163], v[176:179], v[96:99]
	ds_read_b128 v[176:179], v242 offset:36928
	s_waitcnt lgkmcnt(4)
	v_mfma_f32_16x16x32_bf16 v[92:95], v[168:171], v[216:219], v[92:95]
	v_mfma_f32_16x16x32_bf16 v[88:91], v[172:175], v[216:219], v[88:91]
	v_mfma_f32_16x16x32_bf16 v[84:87], v[164:167], v[216:219], v[84:87]
	v_mfma_f32_16x16x32_bf16 v[80:83], v[160:163], v[216:219], v[80:83]
	ds_read_b128 v[216:219], v242 offset:39232
	s_waitcnt lgkmcnt(4)
	v_mfma_f32_16x16x32_bf16 v[76:79], v[168:171], v[188:191], v[76:79]
	v_mfma_f32_16x16x32_bf16 v[72:75], v[172:175], v[188:191], v[72:75]
	v_mfma_f32_16x16x32_bf16 v[68:71], v[164:167], v[188:191], v[68:71]
	v_mfma_f32_16x16x32_bf16 v[64:67], v[160:163], v[188:191], v[64:67]
	ds_read_b128 v[188:191], v242 offset:41536
	s_waitcnt lgkmcnt(4)
	v_mfma_f32_16x16x32_bf16 v[60:63], v[168:171], v[184:187], v[60:63]
	v_mfma_f32_16x16x32_bf16 v[56:59], v[172:175], v[184:187], v[56:59]
	v_mfma_f32_16x16x32_bf16 v[52:55], v[164:167], v[184:187], v[52:55]
	v_mfma_f32_16x16x32_bf16 v[48:51], v[160:163], v[184:187], v[48:51]
	ds_read_b128 v[184:187], v242 offset:43840
	ds_read_b128 v[242:245], v192 offset:64
	s_waitcnt lgkmcnt(5)
	v_mfma_f32_16x16x32_bf16 v[44:47], v[168:171], v[180:183], v[44:47]
	ds_read_b128 v[168:171], v192 offset:2368
	v_mfma_f32_16x16x32_bf16 v[40:43], v[172:175], v[180:183], v[40:43]
	ds_read_b128 v[172:175], v192 offset:4672
	v_mfma_f32_16x16x32_bf16 v[36:39], v[164:167], v[180:183], v[36:39]
	ds_read_b128 v[164:167], v192 offset:6976
	v_mfma_f32_16x16x32_bf16 v[32:35], v[160:163], v[180:183], v[32:35]
	ds_read_b128 v[160:163], v192 offset:9280
	ds_read_b128 v[180:183], v192 offset:11584
	s_waitcnt lgkmcnt(5)
	v_mfma_f32_16x16x32_bf16 v[156:159], v[176:179], v[242:245], v[156:159]
	v_mfma_f32_16x16x32_bf16 v[152:155], v[216:219], v[242:245], v[152:155]
	v_mfma_f32_16x16x32_bf16 v[148:151], v[188:191], v[242:245], v[148:151]
	v_mfma_f32_16x16x32_bf16 v[144:147], v[184:187], v[242:245], v[144:147]
	ds_read_b128 v[242:245], v192 offset:13888
	s_waitcnt lgkmcnt(5)
	v_mfma_f32_16x16x32_bf16 v[140:143], v[176:179], v[168:171], v[140:143]
	v_mfma_f32_16x16x32_bf16 v[136:139], v[216:219], v[168:171], v[136:139]
	v_mfma_f32_16x16x32_bf16 v[132:135], v[188:191], v[168:171], v[132:135]
	v_mfma_f32_16x16x32_bf16 v[128:131], v[184:187], v[168:171], v[128:131]
	ds_read_b128 v[168:171], v192 offset:16192
	s_waitcnt lgkmcnt(5)
	v_mfma_f32_16x16x32_bf16 v[124:127], v[176:179], v[172:175], v[124:127]
	v_mfma_f32_16x16x32_bf16 v[120:123], v[216:219], v[172:175], v[120:123]
	v_mfma_f32_16x16x32_bf16 v[116:119], v[188:191], v[172:175], v[116:119]
	v_mfma_f32_16x16x32_bf16 v[112:115], v[184:187], v[172:175], v[112:115]
	s_bitcmp1_b32 s38, 0
	s_cselect_b32 s1, 0x12000, 0
	v_or_b32_e32 v172, s1, v232
	v_add_u32_e32 v172, v172, v236
	s_waitcnt vmcnt(7)
	ds_write_b128 v172, v[0:3]
	s_waitcnt vmcnt(6)
	ds_write_b128 v172, v[4:7] offset:9216
	s_waitcnt lgkmcnt(6)
	v_mfma_f32_16x16x32_bf16 v[108:111], v[176:179], v[164:167], v[108:111]
	v_mfma_f32_16x16x32_bf16 v[104:107], v[216:219], v[164:167], v[104:107]
	v_mfma_f32_16x16x32_bf16 v[100:103], v[188:191], v[164:167], v[100:103]
	v_mfma_f32_16x16x32_bf16 v[96:99], v[184:187], v[164:167], v[96:99]
	s_waitcnt vmcnt(5)
	ds_write_b128 v172, v[8:11] offset:18432
	s_waitcnt vmcnt(4)
	ds_write_b128 v172, v[12:15] offset:27648
	s_waitcnt lgkmcnt(7)
	v_mfma_f32_16x16x32_bf16 v[92:95], v[176:179], v[160:163], v[92:95]
	v_mfma_f32_16x16x32_bf16 v[88:91], v[216:219], v[160:163], v[88:91]
	v_mfma_f32_16x16x32_bf16 v[84:87], v[188:191], v[160:163], v[84:87]
	v_mfma_f32_16x16x32_bf16 v[80:83], v[184:187], v[160:163], v[80:83]
	s_waitcnt vmcnt(3)
	ds_write_b128 v172, v[16:19] offset:36864
	s_waitcnt vmcnt(2)
	ds_write_b128 v172, v[20:23] offset:46080
	s_waitcnt lgkmcnt(8)
	v_mfma_f32_16x16x32_bf16 v[76:79], v[176:179], v[180:183], v[76:79]
	v_mfma_f32_16x16x32_bf16 v[72:75], v[216:219], v[180:183], v[72:75]
	v_mfma_f32_16x16x32_bf16 v[68:71], v[188:191], v[180:183], v[68:71]
	v_mfma_f32_16x16x32_bf16 v[64:67], v[184:187], v[180:183], v[64:67]
	s_waitcnt vmcnt(1)
	ds_write_b128 v172, v[24:27] offset:55296
	s_waitcnt vmcnt(0)
	ds_write_b128 v172, v[28:31] offset:64512

; #define MFMA16(a, b, c) __builtin_amdgcn_mfma_f32_16x16x32_bf16((a), (b), (c), 0, 0, 0)
;     ...
;         const int h = gi % HG;
; #pragma unroll
;         for (int i = 0; i < FA; ++i)
; #pragma unroll
;           for (int j = 0; j < 4; ++j)
;             acc[h * FA + i][j] = NAT ? MFMA16(fa[gi & 1][i], fb[ks & 1][j], acc[h * FA + i][j]) : MFMA16(fb[ks & 1][j], fa[gi & 1][i], acc[h * FA + i][j]);
;         __builtin_amdgcn_sched_barrier(0);
;       }
;     }
;     if (kt == nk - 1) {
;       int mt, nt; tile_at(jt, mt, nt);
;       f(mt, nt, [&](auto&& a, auto&& bfn, auto&& ep) { ep(acc, wm, wn, lane); });
; #pragma unroll
;       for (int i = 0; i < MI; ++i)
; #pragma unroll
;         for (int j = 0; j < 4; ++j) acc[i][j] = (f32x4){0.f, 0.f, 0.f, 0.f};
;       kt = 0; ++jt;
;     } else ++kt;
.LBB0_2643:
	s_waitcnt lgkmcnt(9)
	v_mfma_f32_16x16x32_bf16 v[60:63], v[176:179], v[242:245], v[60:63]
	v_mfma_f32_16x16x32_bf16 v[56:59], v[216:219], v[242:245], v[56:59]
	v_mfma_f32_16x16x32_bf16 v[52:55], v[188:191], v[242:245], v[52:55]
	v_mfma_f32_16x16x32_bf16 v[48:51], v[184:187], v[242:245], v[48:51]
	s_waitcnt lgkmcnt(8)
	v_mfma_f32_16x16x32_bf16 v[44:47], v[176:179], v[168:171], v[44:47]
	v_mfma_f32_16x16x32_bf16 v[40:43], v[216:219], v[168:171], v[40:43]
	v_mfma_f32_16x16x32_bf16 v[36:39], v[188:191], v[168:171], v[36:39]
	v_mfma_f32_16x16x32_bf16 v[32:35], v[184:187], v[168:171], v[32:35]
	s_waitcnt lgkmcnt(0)
	s_cmp_lg_u32 s39, 55
	s_mov_b64 s[0:1], -1
	s_cbranch_scc0 .LBB0_2645
	s_add_i32 s39, s39, 1
	s_mov_b64 s[0:1], 0
